# residual-GEMM epilogues (w2, gla_out): 7 of 8 second-half residual loads hoisted to the top of the epilogue
# speedup vs baseline: 1.0067x; 1.0060x over previous
.LBB0_1062:
	ds_read_b128 v[128:131], v189
	ds_read_b128 v[132:135], v189 offset:1024
	ds_read_b128 v[136:139], v189 offset:2048
	ds_read_b128 v[140:143], v189 offset:3072
	s_add_u32 s52, s50, 0xfff00080
	s_addc_u32 s53, s51, -1
	s_cmp_eq_u32 s60, 60
	s_cselect_b32 s55, s27, s53
	s_cselect_b32 s54, s37, s52
	s_cselect_b32 s53, s25, s59
	s_cselect_b32 s52, s57, s58
	v_lshl_add_u64 v[184:185], s[50:51], 0, v[160:161]
	s_add_i32 m0, s34, 0xc000
	ds_read_b128 v[144:147], v190
	ds_read_b128 v[148:151], v190 offset:1024
	ds_read_b128 v[168:171], v190 offset:2048
	ds_read_b128 v[172:175], v190 offset:3072
	ds_read_b128 v[176:179], v190 offset:4096
	ds_read_b128 v[180:183], v190 offset:5120
	ds_read_b128 v[192:195], v190 offset:6144
	ds_read_b128 v[196:199], v190 offset:7168
	global_load_lds_dwordx4 v[184:185], off
	v_lshl_add_u64 v[184:185], s[50:51], 0, v[162:163]
	s_add_i32 m0, s34, 0xe000
	s_nop 0
	global_load_lds_dwordx4 v[184:185], off
	s_waitcnt lgkmcnt(8)
	s_barrier
	s_waitcnt lgkmcnt(0)
	s_setprio 1
	s_waitcnt lgkmcnt(0)
	v_mfma_f32_16x16x32_bf16 v[124:127], v[128:131], v[144:147], v[124:127]
	v_mfma_f32_16x16x32_bf16 v[120:123], v[136:139], v[144:147], v[120:123]
	v_mfma_f32_16x16x32_bf16 v[108:111], v[128:131], v[168:171], v[108:111]
	v_mfma_f32_16x16x32_bf16 v[104:107], v[136:139], v[168:171], v[104:107]
	v_mfma_f32_16x16x32_bf16 v[92:95], v[128:131], v[176:179], v[92:95]
	v_mfma_f32_16x16x32_bf16 v[88:91], v[136:139], v[176:179], v[88:91]
	v_mfma_f32_16x16x32_bf16 v[76:79], v[128:131], v[192:195], v[76:79]
	v_mfma_f32_16x16x32_bf16 v[72:75], v[136:139], v[192:195], v[72:75]
	v_mfma_f32_16x16x32_bf16 v[124:127], v[132:135], v[148:151], v[124:127]
	v_mfma_f32_16x16x32_bf16 v[120:123], v[140:143], v[148:151], v[120:123]
	v_mfma_f32_16x16x32_bf16 v[108:111], v[132:135], v[172:175], v[108:111]
	v_mfma_f32_16x16x32_bf16 v[104:107], v[140:143], v[172:175], v[104:107]
	v_mfma_f32_16x16x32_bf16 v[92:95], v[132:135], v[180:183], v[92:95]
	v_mfma_f32_16x16x32_bf16 v[88:91], v[140:143], v[180:183], v[88:91]
	v_mfma_f32_16x16x32_bf16 v[76:79], v[132:135], v[196:199], v[76:79]
	v_mfma_f32_16x16x32_bf16 v[72:75], v[140:143], v[196:199], v[72:75]
	s_setprio 0
	s_barrier
	s_add_i32 s61, s49, s33
	v_lshl_add_u64 v[184:185], s[52:53], 0, v[154:155]
	s_mov_b32 m0, s61
	ds_read_b128 v[200:203], v191
	ds_read_b128 v[206:209], v191 offset:1024
	ds_read_b128 v[210:213], v191 offset:2048
	ds_read_b128 v[214:217], v191 offset:3072
	global_load_lds_dwordx4 v[184:185], off
	v_lshl_add_u64 v[218:219], s[52:53], 0, v[158:159]
	s_add_i32 m0, s61, 0x2000
	s_nop 0
	global_load_lds_dwordx4 v[218:219], off
	s_barrier
	s_waitcnt lgkmcnt(0)
	s_setprio 1
	s_waitcnt lgkmcnt(0)
	v_mfma_f32_16x16x32_bf16 v[116:119], v[200:203], v[144:147], v[116:119]
	v_mfma_f32_16x16x32_bf16 v[112:115], v[210:213], v[144:147], v[112:115]
	v_mfma_f32_16x16x32_bf16 v[100:103], v[200:203], v[168:171], v[100:103]
	v_mfma_f32_16x16x32_bf16 v[96:99], v[210:213], v[168:171], v[96:99]
	v_mfma_f32_16x16x32_bf16 v[84:87], v[200:203], v[176:179], v[84:87]
	v_mfma_f32_16x16x32_bf16 v[80:83], v[210:213], v[176:179], v[80:83]
	v_mfma_f32_16x16x32_bf16 v[68:71], v[200:203], v[192:195], v[68:71]
	v_mfma_f32_16x16x32_bf16 v[64:67], v[210:213], v[192:195], v[64:67]
	v_mfma_f32_16x16x32_bf16 v[116:119], v[206:209], v[148:151], v[116:119]
	v_mfma_f32_16x16x32_bf16 v[112:115], v[214:217], v[148:151], v[112:115]
	v_mfma_f32_16x16x32_bf16 v[100:103], v[206:209], v[172:175], v[100:103]
	v_mfma_f32_16x16x32_bf16 v[96:99], v[214:217], v[172:175], v[96:99]
	v_mfma_f32_16x16x32_bf16 v[84:87], v[206:209], v[180:183], v[84:87]
	v_mfma_f32_16x16x32_bf16 v[80:83], v[214:217], v[180:183], v[80:83]
	v_mfma_f32_16x16x32_bf16 v[68:71], v[206:209], v[196:199], v[68:71]
	v_mfma_f32_16x16x32_bf16 v[64:67], v[214:217], v[196:199], v[64:67]
	s_setprio 0
	s_mov_b32 m0, s34
	v_lshl_add_u64 v[220:221], s[54:55], 0, v[152:153]
	s_barrier
	ds_read_b128 v[144:147], v190 offset:16384
	ds_read_b128 v[148:151], v190 offset:17408
	ds_read_b128 v[168:171], v190 offset:18432
	ds_read_b128 v[172:175], v190 offset:19456
	ds_read_b128 v[176:179], v190 offset:20480
	ds_read_b128 v[180:183], v190 offset:21504
	ds_read_b128 v[192:195], v190 offset:22528
	ds_read_b128 v[196:199], v190 offset:23552
	global_load_lds_dwordx4 v[220:221], off
	v_lshl_add_u64 v[222:223], s[54:55], 0, v[156:157]
	s_mov_b32 m0, s35
	s_nop 0
	global_load_lds_dwordx4 v[222:223], off
	s_barrier
	s_waitcnt lgkmcnt(0)
	s_setprio 1
	s_waitcnt lgkmcnt(0)
	v_mfma_f32_16x16x32_bf16 v[60:63], v[128:131], v[144:147], v[60:63]
	v_mfma_f32_16x16x32_bf16 v[56:59], v[136:139], v[144:147], v[56:59]
	v_mfma_f32_16x16x32_bf16 v[44:47], v[128:131], v[168:171], v[44:47]
	v_mfma_f32_16x16x32_bf16 v[40:43], v[136:139], v[168:171], v[40:43]
	v_mfma_f32_16x16x32_bf16 v[28:31], v[128:131], v[176:179], v[28:31]
	v_mfma_f32_16x16x32_bf16 v[24:27], v[136:139], v[176:179], v[24:27]
	v_mfma_f32_16x16x32_bf16 v[12:15], v[128:131], v[192:195], v[12:15]
	v_mfma_f32_16x16x32_bf16 v[8:11], v[136:139], v[192:195], v[8:11]
	v_mfma_f32_16x16x32_bf16 v[60:63], v[132:135], v[148:151], v[60:63]
	v_mfma_f32_16x16x32_bf16 v[56:59], v[140:143], v[148:151], v[56:59]
	v_mfma_f32_16x16x32_bf16 v[44:47], v[132:135], v[172:175], v[44:47]
	v_mfma_f32_16x16x32_bf16 v[40:43], v[140:143], v[172:175], v[40:43]
	v_mfma_f32_16x16x32_bf16 v[28:31], v[132:135], v[180:183], v[28:31]
	v_mfma_f32_16x16x32_bf16 v[24:27], v[140:143], v[180:183], v[24:27]
	v_mfma_f32_16x16x32_bf16 v[12:15], v[132:135], v[196:199], v[12:15]
	v_mfma_f32_16x16x32_bf16 v[8:11], v[140:143], v[196:199], v[8:11]
	s_setprio 0
	s_barrier
	s_add_u32 s62, s52, 0x100000
	s_addc_u32 s63, s53, 0
	s_add_i32 s61, s56, s33
	v_lshl_add_u64 v[128:129], s[62:63], 0, v[154:155]
	s_mov_b32 m0, s61
	s_nop 0
	global_load_lds_dwordx4 v[128:129], off
	v_lshl_add_u64 v[128:129], s[62:63], 0, v[158:159]
	s_add_i32 m0, s61, 0x2000
	s_nop 0
	global_load_lds_dwordx4 v[128:129], off
	s_waitcnt vmcnt(6)
	s_barrier
	s_setprio 1
	v_mfma_f32_16x16x32_bf16 v[52:55], v[200:203], v[144:147], v[52:55]
	v_mfma_f32_16x16x32_bf16 v[48:51], v[210:213], v[144:147], v[48:51]
	v_mfma_f32_16x16x32_bf16 v[36:39], v[200:203], v[168:171], v[36:39]
	v_mfma_f32_16x16x32_bf16 v[32:35], v[210:213], v[168:171], v[32:35]
	v_mfma_f32_16x16x32_bf16 v[20:23], v[200:203], v[176:179], v[20:23]
	v_mfma_f32_16x16x32_bf16 v[16:19], v[210:213], v[176:179], v[16:19]
	v_mfma_f32_16x16x32_bf16 v[4:7], v[200:203], v[192:195], v[4:7]
	v_mfma_f32_16x16x32_bf16 v[0:3], v[210:213], v[192:195], v[0:3]
	v_mfma_f32_16x16x32_bf16 v[52:55], v[206:209], v[148:151], v[52:55]
	v_mfma_f32_16x16x32_bf16 v[48:51], v[214:217], v[148:151], v[48:51]
	v_mfma_f32_16x16x32_bf16 v[36:39], v[206:209], v[172:175], v[36:39]
	v_mfma_f32_16x16x32_bf16 v[32:35], v[214:217], v[172:175], v[32:35]
	v_mfma_f32_16x16x32_bf16 v[20:23], v[206:209], v[180:183], v[20:23]
	v_mfma_f32_16x16x32_bf16 v[16:19], v[214:217], v[180:183], v[16:19]
	v_mfma_f32_16x16x32_bf16 v[4:7], v[206:209], v[196:199], v[4:7]
	v_mfma_f32_16x16x32_bf16 v[0:3], v[214:217], v[196:199], v[0:3]
	s_setprio 0
	s_add_i32 s61, 0, 0x18000
	v_add_u32_e32 v140, s61, v187
	s_barrier
	ds_read_b128 v[128:131], v140
	ds_read_b128 v[132:135], v140 offset:1024
	ds_read_b128 v[136:139], v140 offset:2048
	ds_read_b128 v[140:143], v140 offset:3072
	s_add_u32 s54, s54, 0x100000
	s_addc_u32 s55, s55, 0
	s_mov_b32 m0, s39
	v_lshl_add_u64 v[200:201], s[54:55], 0, v[152:153]
	ds_read_b128 v[144:147], v190 offset:32768
	ds_read_b128 v[148:151], v190 offset:33792
	ds_read_b128 v[168:171], v190 offset:34816
	ds_read_b128 v[172:175], v190 offset:35840
	ds_read_b128 v[176:179], v190 offset:36864
	ds_read_b128 v[180:183], v190 offset:37888
	ds_read_b128 v[192:195], v190 offset:38912
	ds_read_b128 v[196:199], v190 offset:39936
	global_load_lds_dwordx4 v[200:201], off
	v_lshl_add_u64 v[200:201], s[54:55], 0, v[156:157]
	s_mov_b32 m0, s42
	s_nop 0
	global_load_lds_dwordx4 v[200:201], off
	s_waitcnt lgkmcnt(8)
	s_barrier
	s_waitcnt lgkmcnt(0)
	s_setprio 1
	s_waitcnt lgkmcnt(0)
	v_mfma_f32_16x16x32_bf16 v[124:127], v[128:131], v[144:147], v[124:127]
	v_mfma_f32_16x16x32_bf16 v[120:123], v[136:139], v[144:147], v[120:123]
	v_mfma_f32_16x16x32_bf16 v[108:111], v[128:131], v[168:171], v[108:111]
	v_mfma_f32_16x16x32_bf16 v[104:107], v[136:139], v[168:171], v[104:107]
	v_mfma_f32_16x16x32_bf16 v[92:95], v[128:131], v[176:179], v[92:95]
	v_mfma_f32_16x16x32_bf16 v[88:91], v[136:139], v[176:179], v[88:91]
	v_mfma_f32_16x16x32_bf16 v[76:79], v[128:131], v[192:195], v[76:79]
	v_mfma_f32_16x16x32_bf16 v[72:75], v[136:139], v[192:195], v[72:75]
	v_mfma_f32_16x16x32_bf16 v[124:127], v[132:135], v[148:151], v[124:127]
	v_mfma_f32_16x16x32_bf16 v[120:123], v[140:143], v[148:151], v[120:123]
	v_mfma_f32_16x16x32_bf16 v[108:111], v[132:135], v[172:175], v[108:111]
	v_mfma_f32_16x16x32_bf16 v[104:107], v[140:143], v[172:175], v[104:107]
	v_mfma_f32_16x16x32_bf16 v[92:95], v[132:135], v[180:183], v[92:95]
	v_mfma_f32_16x16x32_bf16 v[88:91], v[140:143], v[180:183], v[88:91]
	v_mfma_f32_16x16x32_bf16 v[76:79], v[132:135], v[196:199], v[76:79]
	v_mfma_f32_16x16x32_bf16 v[72:75], v[140:143], v[196:199], v[72:75]
	s_setprio 0
	s_barrier
	s_add_i32 s54, 0, 0x1c000
	s_add_i32 s55, s61, s33
	v_add_u32_e32 v214, s54, v187
	v_lshl_add_u64 v[184:185], v[184:185], 0, s[18:19]
	s_mov_b32 m0, s55
	ds_read_b128 v[200:203], v214
	ds_read_b128 v[206:209], v214 offset:1024
	ds_read_b128 v[210:213], v214 offset:2048
	ds_read_b128 v[214:217], v214 offset:3072
	global_load_lds_dwordx4 v[184:185], off
	v_lshl_add_u64 v[184:185], v[218:219], 0, s[18:19]
	s_add_i32 m0, s55, 0x2000
	s_nop 0
	global_load_lds_dwordx4 v[184:185], off
	s_barrier
	s_waitcnt lgkmcnt(0)
	s_setprio 1
	s_waitcnt lgkmcnt(0)
	v_mfma_f32_16x16x32_bf16 v[116:119], v[200:203], v[144:147], v[116:119]
	v_mfma_f32_16x16x32_bf16 v[112:115], v[210:213], v[144:147], v[112:115]
	v_mfma_f32_16x16x32_bf16 v[100:103], v[200:203], v[168:171], v[100:103]
	v_mfma_f32_16x16x32_bf16 v[96:99], v[210:213], v[168:171], v[96:99]
	v_mfma_f32_16x16x32_bf16 v[84:87], v[200:203], v[176:179], v[84:87]
	v_mfma_f32_16x16x32_bf16 v[80:83], v[210:213], v[176:179], v[80:83]
	v_mfma_f32_16x16x32_bf16 v[68:71], v[200:203], v[192:195], v[68:71]
	v_mfma_f32_16x16x32_bf16 v[64:67], v[210:213], v[192:195], v[64:67]
	v_mfma_f32_16x16x32_bf16 v[116:119], v[206:209], v[148:151], v[116:119]
	v_mfma_f32_16x16x32_bf16 v[112:115], v[214:217], v[148:151], v[112:115]
	v_mfma_f32_16x16x32_bf16 v[100:103], v[206:209], v[172:175], v[100:103]
	v_mfma_f32_16x16x32_bf16 v[96:99], v[214:217], v[172:175], v[96:99]
	v_mfma_f32_16x16x32_bf16 v[84:87], v[206:209], v[180:183], v[84:87]
	v_mfma_f32_16x16x32_bf16 v[80:83], v[214:217], v[180:183], v[80:83]
	v_mfma_f32_16x16x32_bf16 v[68:71], v[206:209], v[196:199], v[68:71]
	v_mfma_f32_16x16x32_bf16 v[64:67], v[214:217], v[196:199], v[64:67]
	s_setprio 0
	s_mov_b32 m0, s44
	v_lshl_add_u64 v[184:185], v[220:221], 0, s[18:19]
	s_barrier
	ds_read_b128 v[144:147], v190 offset:49152
	ds_read_b128 v[148:151], v190 offset:50176
	ds_read_b128 v[168:171], v190 offset:51200
	ds_read_b128 v[172:175], v190 offset:52224
	ds_read_b128 v[176:179], v190 offset:53248
	ds_read_b128 v[180:183], v190 offset:54272
	ds_read_b128 v[192:195], v190 offset:55296
	ds_read_b128 v[196:199], v190 offset:56320
	global_load_lds_dwordx4 v[184:185], off
	v_lshl_add_u64 v[184:185], v[222:223], 0, s[18:19]
	s_mov_b32 m0, s45
	s_nop 0
	global_load_lds_dwordx4 v[184:185], off
	s_barrier
	s_waitcnt lgkmcnt(0)
	s_setprio 1
	s_waitcnt lgkmcnt(0)
	v_mfma_f32_16x16x32_bf16 v[60:63], v[128:131], v[144:147], v[60:63]
	v_mfma_f32_16x16x32_bf16 v[56:59], v[136:139], v[144:147], v[56:59]
	v_mfma_f32_16x16x32_bf16 v[44:47], v[128:131], v[168:171], v[44:47]
	v_mfma_f32_16x16x32_bf16 v[40:43], v[136:139], v[168:171], v[40:43]
	v_mfma_f32_16x16x32_bf16 v[28:31], v[128:131], v[176:179], v[28:31]
	v_mfma_f32_16x16x32_bf16 v[24:27], v[136:139], v[176:179], v[24:27]
	v_mfma_f32_16x16x32_bf16 v[12:15], v[128:131], v[192:195], v[12:15]
	v_mfma_f32_16x16x32_bf16 v[8:11], v[136:139], v[192:195], v[8:11]
	v_mfma_f32_16x16x32_bf16 v[60:63], v[132:135], v[148:151], v[60:63]
	v_mfma_f32_16x16x32_bf16 v[56:59], v[140:143], v[148:151], v[56:59]
	v_mfma_f32_16x16x32_bf16 v[44:47], v[132:135], v[172:175], v[44:47]
	v_mfma_f32_16x16x32_bf16 v[40:43], v[140:143], v[172:175], v[40:43]
	v_mfma_f32_16x16x32_bf16 v[28:31], v[132:135], v[180:183], v[28:31]
	v_mfma_f32_16x16x32_bf16 v[24:27], v[140:143], v[180:183], v[24:27]
	v_mfma_f32_16x16x32_bf16 v[12:15], v[132:135], v[196:199], v[12:15]
	v_mfma_f32_16x16x32_bf16 v[8:11], v[140:143], v[196:199], v[8:11]
	s_setprio 0
	s_barrier
	s_add_u32 s52, s52, 0x100080
	s_addc_u32 s53, s53, 0
	s_add_i32 s54, s54, s33
	v_lshl_add_u64 v[128:129], s[52:53], 0, v[154:155]
	s_mov_b32 m0, s54
	s_nop 0
	global_load_lds_dwordx4 v[128:129], off
	v_lshl_add_u64 v[128:129], s[52:53], 0, v[158:159]
	s_add_i32 m0, s54, 0x2000
	s_nop 0
	global_load_lds_dwordx4 v[128:129], off
	s_waitcnt vmcnt(6)
	s_barrier
	s_setprio 1
	v_mfma_f32_16x16x32_bf16 v[52:55], v[200:203], v[144:147], v[52:55]
	v_mfma_f32_16x16x32_bf16 v[48:51], v[210:213], v[144:147], v[48:51]
	v_mfma_f32_16x16x32_bf16 v[36:39], v[200:203], v[168:171], v[36:39]
	v_mfma_f32_16x16x32_bf16 v[32:35], v[210:213], v[168:171], v[32:35]
	v_mfma_f32_16x16x32_bf16 v[20:23], v[200:203], v[176:179], v[20:23]
	v_mfma_f32_16x16x32_bf16 v[16:19], v[210:213], v[176:179], v[16:19]
	v_mfma_f32_16x16x32_bf16 v[4:7], v[200:203], v[192:195], v[4:7]
	v_mfma_f32_16x16x32_bf16 v[0:3], v[210:213], v[192:195], v[0:3]
	v_mfma_f32_16x16x32_bf16 v[52:55], v[206:209], v[148:151], v[52:55]
	v_mfma_f32_16x16x32_bf16 v[48:51], v[214:217], v[148:151], v[48:51]
	v_mfma_f32_16x16x32_bf16 v[36:39], v[206:209], v[172:175], v[36:39]
	v_mfma_f32_16x16x32_bf16 v[32:35], v[214:217], v[172:175], v[32:35]
	v_mfma_f32_16x16x32_bf16 v[20:23], v[206:209], v[180:183], v[20:23]
	v_mfma_f32_16x16x32_bf16 v[16:19], v[214:217], v[180:183], v[16:19]
	v_mfma_f32_16x16x32_bf16 v[4:7], v[206:209], v[196:199], v[4:7]
	v_mfma_f32_16x16x32_bf16 v[0:3], v[214:217], v[196:199], v[0:3]
	s_setprio 0
	s_add_i32 s60, s60, 2
	s_add_u32 s50, s50, 0x100
	s_addc_u32 s51, s51, 0
	s_add_u32 s58, s58, 0x100
	s_addc_u32 s59, s59, 0
	s_cmp_gt_u32 s60, 61
	s_barrier
	s_cbranch_scc0 .LBB0_1062
	v_lshl_or_b32 v168, s38, 8, v188
	v_lshl_add_u32 v170, s36, 8, v186
	v_ashrrev_i32_e32 v169, 31, v168
	v_lshlrev_b64 v[202:203], 1, v[168:169]
	v_ashrrev_i32_e32 v171, 31, v170
	v_or_b32_e32 v182, 16, v170
	v_lshl_add_u64 v[172:173], s[14:15], 0, v[202:203]
	v_lshlrev_b64 v[206:207], 11, v[170:171]
	v_ashrrev_i32_e32 v183, 31, v182
	v_or_b32_e32 v178, 32, v170
	v_lshl_add_u64 v[128:129], v[172:173], 0, v[206:207]
	v_lshlrev_b64 v[184:185], 11, v[182:183]
	v_ashrrev_i32_e32 v179, 31, v178
	v_or_b32_e32 v174, 48, v170
	global_load_dwordx4 v[194:197], v[128:129], off
	global_load_dwordx4 v[198:201], v[128:129], off offset:256
	v_lshl_add_u64 v[128:129], v[172:173], 0, v[184:185]
	v_lshlrev_b64 v[180:181], 11, v[178:179]
	v_ashrrev_i32_e32 v175, 31, v174
	global_load_dwordx4 v[148:151], v[128:129], off
	global_load_dwordx4 v[144:147], v[128:129], off offset:256
	v_lshl_add_u64 v[128:129], v[172:173], 0, v[180:181]
	v_lshlrev_b64 v[176:177], 11, v[174:175]
	global_load_dwordx4 v[140:143], v[128:129], off
	global_load_dwordx4 v[136:139], v[128:129], off offset:256
	v_lshl_add_u64 v[128:129], v[172:173], 0, v[176:177]
	global_load_dwordx4 v[132:135], v[128:129], off
	s_nop 0
	global_load_dwordx4 v[128:131], v[128:129], off offset:256
	v_and_b32_e32 v193, 64, v205
	v_xor_b32_e32 v192, 16, v205
	v_add_u32_e32 v208, 64, v193
	v_cmp_lt_i32_e32 vcc, v192, v208
	s_nop 1
	v_cndmask_b32_e32 v192, v205, v192, vcc
	v_lshlrev_b32_e32 v193, 2, v192
	v_xor_b32_e32 v192, 32, v205
	v_cmp_lt_i32_e32 vcc, v192, v208
	s_nop 1
	v_cndmask_b32_e32 v192, v205, v192, vcc
	v_lshlrev_b32_e32 v192, 2, v192
	v_add_u32_e32 v236, 0x80, v170
	v_ashrrev_i32_e32 v237, 31, v236
	v_lshlrev_b64 v[236:237], 11, v[236:237]
	v_lshl_add_u64 v[236:237], v[172:173], 0, v[236:237]
	global_load_dwordx4 v[224:227], v[236:237], off
	global_load_dwordx4 v[228:231], v[236:237], off offset:256
	v_add_u32_e32 v236, 0x90, v170
	v_ashrrev_i32_e32 v237, 31, v236
	v_lshlrev_b64 v[236:237], 11, v[236:237]
	v_lshl_add_u64 v[236:237], v[172:173], 0, v[236:237]
	global_load_dwordx4 v[232:235], v[236:237], off
	global_load_dwordx4 v[240:243], v[236:237], off offset:256
	v_add_u32_e32 v236, 0xa0, v170
	v_ashrrev_i32_e32 v237, 31, v236
	v_lshlrev_b64 v[236:237], 11, v[236:237]
	v_lshl_add_u64 v[236:237], v[172:173], 0, v[236:237]
	global_load_dwordx4 v[244:247], v[236:237], off
	global_load_dwordx4 v[248:251], v[236:237], off offset:256
	v_add_u32_e32 v236, 0xb0, v170
	v_ashrrev_i32_e32 v237, 31, v236
	v_lshlrev_b64 v[236:237], 11, v[236:237]
	v_lshl_add_u64 v[236:237], v[172:173], 0, v[236:237]
	global_load_dwordx4 v[252:255], v[236:237], off
	s_waitcnt vmcnt(0)
	v_lshlrev_b32_e32 v208, 16, v194
	v_and_b32_e32 v209, 0xffff0000, v194
	v_lshlrev_b32_e32 v194, 16, v195
	v_and_b32_e32 v195, 0xffff0000, v195
	v_lshlrev_b32_e32 v210, 16, v196
	v_and_b32_e32 v211, 0xffff0000, v196
	v_lshlrev_b32_e32 v196, 16, v197
	v_and_b32_e32 v197, 0xffff0000, v197
	v_pk_add_f32 v[126:127], v[126:127], v[194:195]
	v_pk_add_f32 v[194:195], v[122:123], v[196:197]
	v_pk_add_f32 v[196:197], v[120:121], v[210:211]
	v_pk_add_f32 v[124:125], v[124:125], v[208:209]
	v_cvt_pk_bf16_f32 v122, v196, v197
	v_mul_f32_e32 v196, v196, v196
	v_cvt_pk_bf16_f32 v120, v124, v125
	v_fmac_f32_e32 v196, v124, v124
	v_mul_f32_e32 v124, v197, v197
	v_fmac_f32_e32 v124, v125, v125
	v_mul_f32_e32 v125, v194, v194
	v_add_f32_e32 v124, v196, v124
	v_fmac_f32_e32 v125, v126, v126
	v_add_f32_e32 v124, v125, v124
	v_mul_f32_e32 v125, v195, v195
	v_cvt_pk_bf16_f32 v121, v126, v127
	v_cvt_pk_bf16_f32 v123, v194, v195
	v_fmac_f32_e32 v125, v127, v127
	v_lshlrev_b32_e32 v126, 16, v199
	v_and_b32_e32 v127, 0xffff0000, v199
	v_lshlrev_b32_e32 v194, 16, v200
	v_and_b32_e32 v195, 0xffff0000, v200
	v_add_f32_e32 v208, v125, v124
	v_lshlrev_b32_e32 v124, 16, v198
	v_and_b32_e32 v125, 0xffff0000, v198
	v_pk_add_f32 v[118:119], v[118:119], v[126:127]
	v_pk_add_f32 v[126:127], v[112:113], v[194:195]
	v_pk_add_f32 v[116:117], v[116:117], v[124:125]
	v_mul_f32_e32 v112, v126, v126
	v_lshlrev_b32_e32 v196, 16, v201
	v_and_b32_e32 v197, 0xffff0000, v201
	v_fmac_f32_e32 v112, v116, v116
	v_mul_f32_e32 v113, v127, v127
	v_pk_add_f32 v[124:125], v[114:115], v[196:197]
	v_add_f32_e32 v112, v112, v208
	v_fmac_f32_e32 v113, v117, v117
	v_add_f32_e32 v112, v113, v112
	v_mul_f32_e32 v113, v124, v124
	v_fmac_f32_e32 v113, v118, v118
	v_add_f32_e32 v112, v113, v112
	v_mul_f32_e32 v113, v125, v125
	v_fmac_f32_e32 v113, v119, v119
	v_add_f32_e32 v115, v113, v112
	ds_bpermute_b32 v196, v193, v115
	v_lshl_add_u64 v[112:113], s[14:15], 0, v[206:207]
	v_lshl_add_u64 v[194:195], v[112:113], 0, v[202:203]
	v_cvt_pk_bf16_f32 v114, v116, v117
	v_cvt_pk_bf16_f32 v116, v126, v127
	s_waitcnt lgkmcnt(0)
	v_add_f32_e32 v112, v115, v196
	ds_bpermute_b32 v113, v192, v112
	v_cvt_pk_bf16_f32 v115, v118, v119
	v_cvt_pk_bf16_f32 v117, v124, v125
	global_store_dwordx4 v[194:195], v[120:123], off
	global_store_dwordx4 v[194:195], v[114:117], off offset:256
	s_and_saveexec_b64 s[36:37], s[8:9]
	s_cbranch_execz .LBB0_1065
	s_waitcnt lgkmcnt(0)
	v_add_f32_e32 v112, v112, v113
	v_mul_f32_e32 v112, 0x4b800000, v112
	v_trunc_f32_e32 v112, v112
	v_mul_f32_e32 v113, 0x2f800000, v112
	v_floor_f32_e32 v113, v113
	v_fmac_f32_e32 v112, 0xcf800000, v113
	v_cvt_u32_f32_e32 v112, v112
	v_cvt_u32_f32_e32 v113, v113
	v_lshl_add_u64 v[114:115], v[170:171], 3, s[16:17]
	global_atomic_add_x2 v[114:115], v[112:113], off

.LBB0_1071:
	s_or_b64 exec, exec, s[36:37]
	v_add_u32_e32 v100, 0x80, v170
	v_ashrrev_i32_e32 v101, 31, v100
	v_add_u32_e32 v96, 0x90, v170
	v_lshlrev_b64 v[110:111], 11, v[100:101]
	v_ashrrev_i32_e32 v97, 31, v96
	v_add_u32_e32 v92, 0xa0, v170
	s_waitcnt lgkmcnt(0)
	v_lshl_add_u64 v[64:65], v[172:173], 0, v[110:111]
	v_lshlrev_b64 v[98:99], 11, v[96:97]
	v_ashrrev_i32_e32 v93, 31, v92
	v_add_u32_e32 v88, 0xb0, v170
	v_mov_b32_e32 v102, v224
	v_mov_b32_e32 v103, v225
	v_mov_b32_e32 v104, v226
	v_mov_b32_e32 v105, v227
	v_mov_b32_e32 v106, v228
	v_mov_b32_e32 v107, v229
	v_mov_b32_e32 v108, v230
	v_mov_b32_e32 v109, v231
	v_lshl_add_u64 v[64:65], v[172:173], 0, v[98:99]
	v_lshlrev_b64 v[94:95], 11, v[92:93]
	v_ashrrev_i32_e32 v89, 31, v88
	v_mov_b32_e32 v84, v232
	v_mov_b32_e32 v85, v233
	v_mov_b32_e32 v86, v234
	v_mov_b32_e32 v87, v235
	v_mov_b32_e32 v80, v240
	v_mov_b32_e32 v81, v241
	v_mov_b32_e32 v82, v242
	v_mov_b32_e32 v83, v243
	v_lshl_add_u64 v[64:65], v[172:173], 0, v[94:95]
	v_lshlrev_b64 v[90:91], 11, v[88:89]
	v_mov_b32_e32 v76, v244
	v_mov_b32_e32 v77, v245
	v_mov_b32_e32 v78, v246
	v_mov_b32_e32 v79, v247
	v_mov_b32_e32 v72, v248
	v_mov_b32_e32 v73, v249
	v_mov_b32_e32 v74, v250
	v_mov_b32_e32 v75, v251
	v_lshl_add_u64 v[64:65], v[172:173], 0, v[90:91]
	v_mov_b32_e32 v68, v252
	v_mov_b32_e32 v69, v253
	v_mov_b32_e32 v70, v254
	v_mov_b32_e32 v71, v255
	s_nop 0
	global_load_dwordx4 v[64:67], v[64:65], off offset:256
	s_waitcnt vmcnt(7)
	v_lshlrev_b32_e32 v112, 16, v102
	v_and_b32_e32 v113, 0xffff0000, v102
	v_lshlrev_b32_e32 v102, 16, v103
	v_and_b32_e32 v103, 0xffff0000, v103
	v_lshlrev_b32_e32 v114, 16, v104
	v_and_b32_e32 v115, 0xffff0000, v104
	v_lshlrev_b32_e32 v104, 16, v105
	v_and_b32_e32 v105, 0xffff0000, v105
	v_pk_add_f32 v[62:63], v[62:63], v[102:103]
	v_pk_add_f32 v[102:103], v[58:59], v[104:105]
	v_pk_add_f32 v[104:105], v[56:57], v[114:115]
	v_pk_add_f32 v[60:61], v[60:61], v[112:113]
	v_cvt_pk_bf16_f32 v58, v104, v105
	v_mul_f32_e32 v104, v104, v104
	v_cvt_pk_bf16_f32 v56, v60, v61
	v_fmac_f32_e32 v104, v60, v60
	v_mul_f32_e32 v60, v105, v105
	v_fmac_f32_e32 v60, v61, v61
	v_mul_f32_e32 v61, v102, v102
	v_add_f32_e32 v60, v104, v60
	v_fmac_f32_e32 v61, v62, v62
	v_add_f32_e32 v60, v61, v60
	v_mul_f32_e32 v61, v103, v103
	v_cvt_pk_bf16_f32 v57, v62, v63
	v_cvt_pk_bf16_f32 v59, v102, v103
	v_fmac_f32_e32 v61, v63, v63
	s_waitcnt vmcnt(6)
	v_lshlrev_b32_e32 v62, 16, v107
	v_and_b32_e32 v63, 0xffff0000, v107
	v_lshlrev_b32_e32 v102, 16, v108
	v_and_b32_e32 v103, 0xffff0000, v108
	v_add_f32_e32 v112, v61, v60
	v_lshlrev_b32_e32 v60, 16, v106
	v_and_b32_e32 v61, 0xffff0000, v106
	v_pk_add_f32 v[54:55], v[54:55], v[62:63]
	v_pk_add_f32 v[62:63], v[48:49], v[102:103]
	v_pk_add_f32 v[52:53], v[52:53], v[60:61]
	v_mul_f32_e32 v48, v62, v62
	v_lshlrev_b32_e32 v104, 16, v109
	v_and_b32_e32 v105, 0xffff0000, v109
	v_fmac_f32_e32 v48, v52, v52
	v_mul_f32_e32 v49, v63, v63
	v_pk_add_f32 v[60:61], v[50:51], v[104:105]
	v_add_f32_e32 v48, v48, v112
	v_fmac_f32_e32 v49, v53, v53
	v_add_f32_e32 v48, v49, v48
	v_mul_f32_e32 v49, v60, v60
	v_fmac_f32_e32 v49, v54, v54
	v_add_f32_e32 v48, v49, v48
	v_mul_f32_e32 v49, v61, v61
	v_fmac_f32_e32 v49, v55, v55
	v_add_f32_e32 v51, v49, v48
	ds_bpermute_b32 v104, v193, v51
	v_lshl_add_u64 v[48:49], s[14:15], 0, v[110:111]
	v_lshl_add_u64 v[102:103], v[168:169], 1, v[48:49]
	v_cvt_pk_bf16_f32 v50, v52, v53
	v_cvt_pk_bf16_f32 v52, v62, v63
	s_waitcnt lgkmcnt(0)
	v_add_f32_e32 v48, v51, v104
	ds_bpermute_b32 v49, v192, v48
	v_cvt_pk_bf16_f32 v51, v54, v55
	v_cvt_pk_bf16_f32 v53, v60, v61
	global_store_dwordx4 v[102:103], v[56:59], off
	global_store_dwordx4 v[102:103], v[50:53], off offset:256
	s_and_saveexec_b64 s[36:37], s[8:9]
	s_cbranch_execz .LBB0_1073
	s_waitcnt lgkmcnt(0)
	v_add_f32_e32 v48, v48, v49
	v_mul_f32_e32 v48, 0x4b800000, v48
	v_trunc_f32_e32 v48, v48
	v_mul_f32_e32 v49, 0x2f800000, v48
	v_floor_f32_e32 v49, v49
	v_fmac_f32_e32 v48, 0xcf800000, v49
	v_cvt_u32_f32_e32 v48, v48
	v_cvt_u32_f32_e32 v49, v49
	v_lshl_add_u64 v[50:51], v[100:101], 3, s[16:17]
	global_atomic_add_x2 v[50:51], v[48:49], off

.LBB0_1894:
	ds_read_b128 v[128:131], v189
	ds_read_b128 v[132:135], v189 offset:1024
	ds_read_b128 v[136:139], v189 offset:2048
	ds_read_b128 v[140:143], v189 offset:3072
	s_add_u32 s42, s40, 0xfffc0080
	s_addc_u32 s43, s41, -1
	s_cmp_eq_u32 s57, 12
	s_cselect_b32 s45, s29, s43
	s_cselect_b32 s44, s37, s42
	s_cselect_b32 s43, s27, s56
	s_cselect_b32 s42, s54, s55
	v_lshl_add_u64 v[184:185], s[40:41], 0, v[160:161]
	s_add_i32 m0, s20, 0xc000
	ds_read_b128 v[144:147], v190
	ds_read_b128 v[148:151], v190 offset:1024
	ds_read_b128 v[168:171], v190 offset:2048
	ds_read_b128 v[172:175], v190 offset:3072
	ds_read_b128 v[176:179], v190 offset:4096
	ds_read_b128 v[180:183], v190 offset:5120
	ds_read_b128 v[192:195], v190 offset:6144
	ds_read_b128 v[196:199], v190 offset:7168
	global_load_lds_dwordx4 v[184:185], off
	v_lshl_add_u64 v[184:185], s[40:41], 0, v[162:163]
	s_add_i32 m0, s20, 0xe000
	s_nop 0
	global_load_lds_dwordx4 v[184:185], off
	s_waitcnt lgkmcnt(8)
	s_barrier
	s_waitcnt lgkmcnt(0)
	s_setprio 1
	s_waitcnt lgkmcnt(0)
	v_mfma_f32_16x16x32_bf16 v[124:127], v[128:131], v[144:147], v[124:127]
	v_mfma_f32_16x16x32_bf16 v[120:123], v[136:139], v[144:147], v[120:123]
	v_mfma_f32_16x16x32_bf16 v[108:111], v[128:131], v[168:171], v[108:111]
	v_mfma_f32_16x16x32_bf16 v[104:107], v[136:139], v[168:171], v[104:107]
	v_mfma_f32_16x16x32_bf16 v[92:95], v[128:131], v[176:179], v[92:95]
	v_mfma_f32_16x16x32_bf16 v[88:91], v[136:139], v[176:179], v[88:91]
	v_mfma_f32_16x16x32_bf16 v[76:79], v[128:131], v[192:195], v[76:79]
	v_mfma_f32_16x16x32_bf16 v[72:75], v[136:139], v[192:195], v[72:75]
	v_mfma_f32_16x16x32_bf16 v[124:127], v[132:135], v[148:151], v[124:127]
	v_mfma_f32_16x16x32_bf16 v[120:123], v[140:143], v[148:151], v[120:123]
	v_mfma_f32_16x16x32_bf16 v[108:111], v[132:135], v[172:175], v[108:111]
	v_mfma_f32_16x16x32_bf16 v[104:107], v[140:143], v[172:175], v[104:107]
	v_mfma_f32_16x16x32_bf16 v[92:95], v[132:135], v[180:183], v[92:95]
	v_mfma_f32_16x16x32_bf16 v[88:91], v[140:143], v[180:183], v[88:91]
	v_mfma_f32_16x16x32_bf16 v[76:79], v[132:135], v[196:199], v[76:79]
	v_mfma_f32_16x16x32_bf16 v[72:75], v[140:143], v[196:199], v[72:75]
	s_setprio 0
	s_barrier
	s_add_i32 s58, s52, s3
	v_lshl_add_u64 v[184:185], s[42:43], 0, v[154:155]
	s_mov_b32 m0, s58
	ds_read_b128 v[200:203], v191
	ds_read_b128 v[206:209], v191 offset:1024
	ds_read_b128 v[210:213], v191 offset:2048
	ds_read_b128 v[214:217], v191 offset:3072
	global_load_lds_dwordx4 v[184:185], off
	v_lshl_add_u64 v[218:219], s[42:43], 0, v[158:159]
	s_add_i32 m0, s58, 0x2000
	s_nop 0
	global_load_lds_dwordx4 v[218:219], off
	s_barrier
	s_waitcnt lgkmcnt(0)
	s_setprio 1
	s_waitcnt lgkmcnt(0)
	v_mfma_f32_16x16x32_bf16 v[116:119], v[200:203], v[144:147], v[116:119]
	v_mfma_f32_16x16x32_bf16 v[112:115], v[210:213], v[144:147], v[112:115]
	v_mfma_f32_16x16x32_bf16 v[100:103], v[200:203], v[168:171], v[100:103]
	v_mfma_f32_16x16x32_bf16 v[96:99], v[210:213], v[168:171], v[96:99]
	v_mfma_f32_16x16x32_bf16 v[84:87], v[200:203], v[176:179], v[84:87]
	v_mfma_f32_16x16x32_bf16 v[80:83], v[210:213], v[176:179], v[80:83]
	v_mfma_f32_16x16x32_bf16 v[68:71], v[200:203], v[192:195], v[68:71]
	v_mfma_f32_16x16x32_bf16 v[64:67], v[210:213], v[192:195], v[64:67]
	v_mfma_f32_16x16x32_bf16 v[116:119], v[206:209], v[148:151], v[116:119]
	v_mfma_f32_16x16x32_bf16 v[112:115], v[214:217], v[148:151], v[112:115]
	v_mfma_f32_16x16x32_bf16 v[100:103], v[206:209], v[172:175], v[100:103]
	v_mfma_f32_16x16x32_bf16 v[96:99], v[214:217], v[172:175], v[96:99]
	v_mfma_f32_16x16x32_bf16 v[84:87], v[206:209], v[180:183], v[84:87]
	v_mfma_f32_16x16x32_bf16 v[80:83], v[214:217], v[180:183], v[80:83]
	v_mfma_f32_16x16x32_bf16 v[68:71], v[206:209], v[196:199], v[68:71]
	v_mfma_f32_16x16x32_bf16 v[64:67], v[214:217], v[196:199], v[64:67]
	s_setprio 0
	s_mov_b32 m0, s20
	v_lshl_add_u64 v[220:221], s[44:45], 0, v[152:153]
	s_barrier
	ds_read_b128 v[144:147], v190 offset:16384
	ds_read_b128 v[148:151], v190 offset:17408
	ds_read_b128 v[168:171], v190 offset:18432
	ds_read_b128 v[172:175], v190 offset:19456
	ds_read_b128 v[176:179], v190 offset:20480
	ds_read_b128 v[180:183], v190 offset:21504
	ds_read_b128 v[192:195], v190 offset:22528
	ds_read_b128 v[196:199], v190 offset:23552
	global_load_lds_dwordx4 v[220:221], off
	v_lshl_add_u64 v[222:223], s[44:45], 0, v[156:157]
	s_mov_b32 m0, s21
	s_nop 0
	global_load_lds_dwordx4 v[222:223], off
	s_barrier
	s_waitcnt lgkmcnt(0)
	s_setprio 1
	s_waitcnt lgkmcnt(0)
	v_mfma_f32_16x16x32_bf16 v[60:63], v[128:131], v[144:147], v[60:63]
	v_mfma_f32_16x16x32_bf16 v[56:59], v[136:139], v[144:147], v[56:59]
	v_mfma_f32_16x16x32_bf16 v[44:47], v[128:131], v[168:171], v[44:47]
	v_mfma_f32_16x16x32_bf16 v[40:43], v[136:139], v[168:171], v[40:43]
	v_mfma_f32_16x16x32_bf16 v[28:31], v[128:131], v[176:179], v[28:31]
	v_mfma_f32_16x16x32_bf16 v[24:27], v[136:139], v[176:179], v[24:27]
	v_mfma_f32_16x16x32_bf16 v[12:15], v[128:131], v[192:195], v[12:15]
	v_mfma_f32_16x16x32_bf16 v[8:11], v[136:139], v[192:195], v[8:11]
	v_mfma_f32_16x16x32_bf16 v[60:63], v[132:135], v[148:151], v[60:63]
	v_mfma_f32_16x16x32_bf16 v[56:59], v[140:143], v[148:151], v[56:59]
	v_mfma_f32_16x16x32_bf16 v[44:47], v[132:135], v[172:175], v[44:47]
	v_mfma_f32_16x16x32_bf16 v[40:43], v[140:143], v[172:175], v[40:43]
	v_mfma_f32_16x16x32_bf16 v[28:31], v[132:135], v[180:183], v[28:31]
	v_mfma_f32_16x16x32_bf16 v[24:27], v[140:143], v[180:183], v[24:27]
	v_mfma_f32_16x16x32_bf16 v[12:15], v[132:135], v[196:199], v[12:15]
	v_mfma_f32_16x16x32_bf16 v[8:11], v[140:143], v[196:199], v[8:11]
	s_setprio 0
	s_barrier
	s_add_u32 s58, s42, 0x40000
	s_addc_u32 s59, s43, 0
	s_add_i32 s60, s53, s3
	v_lshl_add_u64 v[128:129], s[58:59], 0, v[154:155]
	s_mov_b32 m0, s60
	s_nop 0
	global_load_lds_dwordx4 v[128:129], off
	v_lshl_add_u64 v[128:129], s[58:59], 0, v[158:159]
	s_add_i32 m0, s60, 0x2000
	s_nop 0
	global_load_lds_dwordx4 v[128:129], off
	s_waitcnt vmcnt(6)
	s_barrier
	s_setprio 1
	v_mfma_f32_16x16x32_bf16 v[52:55], v[200:203], v[144:147], v[52:55]
	v_mfma_f32_16x16x32_bf16 v[48:51], v[210:213], v[144:147], v[48:51]
	v_mfma_f32_16x16x32_bf16 v[36:39], v[200:203], v[168:171], v[36:39]
	v_mfma_f32_16x16x32_bf16 v[32:35], v[210:213], v[168:171], v[32:35]
	v_mfma_f32_16x16x32_bf16 v[20:23], v[200:203], v[176:179], v[20:23]
	v_mfma_f32_16x16x32_bf16 v[16:19], v[210:213], v[176:179], v[16:19]
	v_mfma_f32_16x16x32_bf16 v[4:7], v[200:203], v[192:195], v[4:7]
	v_mfma_f32_16x16x32_bf16 v[0:3], v[210:213], v[192:195], v[0:3]
	v_mfma_f32_16x16x32_bf16 v[52:55], v[206:209], v[148:151], v[52:55]
	v_mfma_f32_16x16x32_bf16 v[48:51], v[214:217], v[148:151], v[48:51]
	v_mfma_f32_16x16x32_bf16 v[36:39], v[206:209], v[172:175], v[36:39]
	v_mfma_f32_16x16x32_bf16 v[32:35], v[214:217], v[172:175], v[32:35]
	v_mfma_f32_16x16x32_bf16 v[20:23], v[206:209], v[180:183], v[20:23]
	v_mfma_f32_16x16x32_bf16 v[16:19], v[214:217], v[180:183], v[16:19]
	v_mfma_f32_16x16x32_bf16 v[4:7], v[206:209], v[196:199], v[4:7]
	v_mfma_f32_16x16x32_bf16 v[0:3], v[214:217], v[196:199], v[0:3]
	s_setprio 0
	s_add_i32 s58, 0, 0x18000
	v_add_u32_e32 v140, s58, v187
	s_barrier
	ds_read_b128 v[128:131], v140
	ds_read_b128 v[132:135], v140 offset:1024
	ds_read_b128 v[136:139], v140 offset:2048
	ds_read_b128 v[140:143], v140 offset:3072
	s_add_u32 s44, s44, 0x40000
	s_addc_u32 s45, s45, 0
	s_mov_b32 m0, s33
	v_lshl_add_u64 v[200:201], s[44:45], 0, v[152:153]
	ds_read_b128 v[144:147], v190 offset:32768
	ds_read_b128 v[148:151], v190 offset:33792
	ds_read_b128 v[168:171], v190 offset:34816
	ds_read_b128 v[172:175], v190 offset:35840
	ds_read_b128 v[176:179], v190 offset:36864
	ds_read_b128 v[180:183], v190 offset:37888
	ds_read_b128 v[192:195], v190 offset:38912
	ds_read_b128 v[196:199], v190 offset:39936
	global_load_lds_dwordx4 v[200:201], off
	v_lshl_add_u64 v[200:201], s[44:45], 0, v[156:157]
	s_mov_b32 m0, s39
	s_nop 0
	global_load_lds_dwordx4 v[200:201], off
	s_waitcnt lgkmcnt(8)
	s_barrier
	s_waitcnt lgkmcnt(0)
	s_setprio 1
	s_waitcnt lgkmcnt(0)
	v_mfma_f32_16x16x32_bf16 v[124:127], v[128:131], v[144:147], v[124:127]
	v_mfma_f32_16x16x32_bf16 v[120:123], v[136:139], v[144:147], v[120:123]
	v_mfma_f32_16x16x32_bf16 v[108:111], v[128:131], v[168:171], v[108:111]
	v_mfma_f32_16x16x32_bf16 v[104:107], v[136:139], v[168:171], v[104:107]
	v_mfma_f32_16x16x32_bf16 v[92:95], v[128:131], v[176:179], v[92:95]
	v_mfma_f32_16x16x32_bf16 v[88:91], v[136:139], v[176:179], v[88:91]
	v_mfma_f32_16x16x32_bf16 v[76:79], v[128:131], v[192:195], v[76:79]
	v_mfma_f32_16x16x32_bf16 v[72:75], v[136:139], v[192:195], v[72:75]
	v_mfma_f32_16x16x32_bf16 v[124:127], v[132:135], v[148:151], v[124:127]
	v_mfma_f32_16x16x32_bf16 v[120:123], v[140:143], v[148:151], v[120:123]
	v_mfma_f32_16x16x32_bf16 v[108:111], v[132:135], v[172:175], v[108:111]
	v_mfma_f32_16x16x32_bf16 v[104:107], v[140:143], v[172:175], v[104:107]
	v_mfma_f32_16x16x32_bf16 v[92:95], v[132:135], v[180:183], v[92:95]
	v_mfma_f32_16x16x32_bf16 v[88:91], v[140:143], v[180:183], v[88:91]
	v_mfma_f32_16x16x32_bf16 v[76:79], v[132:135], v[196:199], v[76:79]
	v_mfma_f32_16x16x32_bf16 v[72:75], v[140:143], v[196:199], v[72:75]
	s_setprio 0
	s_barrier
	s_add_i32 s44, 0, 0x1c000
	s_add_i32 s45, s58, s3
	v_add_u32_e32 v214, s44, v187
	v_lshl_add_u64 v[184:185], v[184:185], 0, s[24:25]
	s_mov_b32 m0, s45
	ds_read_b128 v[200:203], v214
	ds_read_b128 v[206:209], v214 offset:1024
	ds_read_b128 v[210:213], v214 offset:2048
	ds_read_b128 v[214:217], v214 offset:3072
	global_load_lds_dwordx4 v[184:185], off
	v_lshl_add_u64 v[184:185], v[218:219], 0, s[24:25]
	s_add_i32 m0, s45, 0x2000
	s_nop 0
	global_load_lds_dwordx4 v[184:185], off
	s_barrier
	s_waitcnt lgkmcnt(0)
	s_setprio 1
	s_waitcnt lgkmcnt(0)
	v_mfma_f32_16x16x32_bf16 v[116:119], v[200:203], v[144:147], v[116:119]
	v_mfma_f32_16x16x32_bf16 v[112:115], v[210:213], v[144:147], v[112:115]
	v_mfma_f32_16x16x32_bf16 v[100:103], v[200:203], v[168:171], v[100:103]
	v_mfma_f32_16x16x32_bf16 v[96:99], v[210:213], v[168:171], v[96:99]
	v_mfma_f32_16x16x32_bf16 v[84:87], v[200:203], v[176:179], v[84:87]
	v_mfma_f32_16x16x32_bf16 v[80:83], v[210:213], v[176:179], v[80:83]
	v_mfma_f32_16x16x32_bf16 v[68:71], v[200:203], v[192:195], v[68:71]
	v_mfma_f32_16x16x32_bf16 v[64:67], v[210:213], v[192:195], v[64:67]
	v_mfma_f32_16x16x32_bf16 v[116:119], v[206:209], v[148:151], v[116:119]
	v_mfma_f32_16x16x32_bf16 v[112:115], v[214:217], v[148:151], v[112:115]
	v_mfma_f32_16x16x32_bf16 v[100:103], v[206:209], v[172:175], v[100:103]
	v_mfma_f32_16x16x32_bf16 v[96:99], v[214:217], v[172:175], v[96:99]
	v_mfma_f32_16x16x32_bf16 v[84:87], v[206:209], v[180:183], v[84:87]
	v_mfma_f32_16x16x32_bf16 v[80:83], v[214:217], v[180:183], v[80:83]
	v_mfma_f32_16x16x32_bf16 v[68:71], v[206:209], v[196:199], v[68:71]
	v_mfma_f32_16x16x32_bf16 v[64:67], v[214:217], v[196:199], v[64:67]
	s_setprio 0
	s_mov_b32 m0, s47
	v_lshl_add_u64 v[184:185], v[220:221], 0, s[24:25]
	s_barrier
	ds_read_b128 v[144:147], v190 offset:49152
	ds_read_b128 v[148:151], v190 offset:50176
	ds_read_b128 v[168:171], v190 offset:51200
	ds_read_b128 v[172:175], v190 offset:52224
	ds_read_b128 v[176:179], v190 offset:53248
	ds_read_b128 v[180:183], v190 offset:54272
	ds_read_b128 v[192:195], v190 offset:55296
	ds_read_b128 v[196:199], v190 offset:56320
	global_load_lds_dwordx4 v[184:185], off
	v_lshl_add_u64 v[184:185], v[222:223], 0, s[24:25]
	s_mov_b32 m0, s48
	s_nop 0
	global_load_lds_dwordx4 v[184:185], off
	s_barrier
	s_waitcnt lgkmcnt(0)
	s_setprio 1
	s_waitcnt lgkmcnt(0)
	v_mfma_f32_16x16x32_bf16 v[60:63], v[128:131], v[144:147], v[60:63]
	v_mfma_f32_16x16x32_bf16 v[56:59], v[136:139], v[144:147], v[56:59]
	v_mfma_f32_16x16x32_bf16 v[44:47], v[128:131], v[168:171], v[44:47]
	v_mfma_f32_16x16x32_bf16 v[40:43], v[136:139], v[168:171], v[40:43]
	v_mfma_f32_16x16x32_bf16 v[28:31], v[128:131], v[176:179], v[28:31]
	v_mfma_f32_16x16x32_bf16 v[24:27], v[136:139], v[176:179], v[24:27]
	v_mfma_f32_16x16x32_bf16 v[12:15], v[128:131], v[192:195], v[12:15]
	v_mfma_f32_16x16x32_bf16 v[8:11], v[136:139], v[192:195], v[8:11]
	v_mfma_f32_16x16x32_bf16 v[60:63], v[132:135], v[148:151], v[60:63]
	v_mfma_f32_16x16x32_bf16 v[56:59], v[140:143], v[148:151], v[56:59]
	v_mfma_f32_16x16x32_bf16 v[44:47], v[132:135], v[172:175], v[44:47]
	v_mfma_f32_16x16x32_bf16 v[40:43], v[140:143], v[172:175], v[40:43]
	v_mfma_f32_16x16x32_bf16 v[28:31], v[132:135], v[180:183], v[28:31]
	v_mfma_f32_16x16x32_bf16 v[24:27], v[140:143], v[180:183], v[24:27]
	v_mfma_f32_16x16x32_bf16 v[12:15], v[132:135], v[196:199], v[12:15]
	v_mfma_f32_16x16x32_bf16 v[8:11], v[140:143], v[196:199], v[8:11]
	s_setprio 0
	s_barrier
	s_add_u32 s42, s42, 0x40080
	s_addc_u32 s43, s43, 0
	s_add_i32 s44, s44, s3
	v_lshl_add_u64 v[128:129], s[42:43], 0, v[154:155]
	s_mov_b32 m0, s44
	s_nop 0
	global_load_lds_dwordx4 v[128:129], off
	v_lshl_add_u64 v[128:129], s[42:43], 0, v[158:159]
	s_add_i32 m0, s44, 0x2000
	s_nop 0
	global_load_lds_dwordx4 v[128:129], off
	s_waitcnt vmcnt(6)
	s_barrier
	s_setprio 1
	v_mfma_f32_16x16x32_bf16 v[52:55], v[200:203], v[144:147], v[52:55]
	v_mfma_f32_16x16x32_bf16 v[48:51], v[210:213], v[144:147], v[48:51]
	v_mfma_f32_16x16x32_bf16 v[36:39], v[200:203], v[168:171], v[36:39]
	v_mfma_f32_16x16x32_bf16 v[32:35], v[210:213], v[168:171], v[32:35]
	v_mfma_f32_16x16x32_bf16 v[20:23], v[200:203], v[176:179], v[20:23]
	v_mfma_f32_16x16x32_bf16 v[16:19], v[210:213], v[176:179], v[16:19]
	v_mfma_f32_16x16x32_bf16 v[4:7], v[200:203], v[192:195], v[4:7]
	v_mfma_f32_16x16x32_bf16 v[0:3], v[210:213], v[192:195], v[0:3]
	v_mfma_f32_16x16x32_bf16 v[52:55], v[206:209], v[148:151], v[52:55]
	v_mfma_f32_16x16x32_bf16 v[48:51], v[214:217], v[148:151], v[48:51]
	v_mfma_f32_16x16x32_bf16 v[36:39], v[206:209], v[172:175], v[36:39]
	v_mfma_f32_16x16x32_bf16 v[32:35], v[214:217], v[172:175], v[32:35]
	v_mfma_f32_16x16x32_bf16 v[20:23], v[206:209], v[180:183], v[20:23]
	v_mfma_f32_16x16x32_bf16 v[16:19], v[214:217], v[180:183], v[16:19]
	v_mfma_f32_16x16x32_bf16 v[4:7], v[206:209], v[196:199], v[4:7]
	v_mfma_f32_16x16x32_bf16 v[0:3], v[214:217], v[196:199], v[0:3]
	s_setprio 0
	s_add_i32 s57, s57, 2
	s_add_u32 s40, s40, 0x100
	s_addc_u32 s41, s41, 0
	s_add_u32 s55, s55, 0x100
	s_addc_u32 s56, s56, 0
	s_cmp_gt_u32 s57, 13
	s_barrier
	s_cbranch_scc0 .LBB0_1894
	v_lshl_or_b32 v168, s38, 8, v188
	v_lshl_add_u32 v170, s36, 8, v186
	v_ashrrev_i32_e32 v169, 31, v168
	v_lshlrev_b64 v[202:203], 1, v[168:169]
	v_ashrrev_i32_e32 v171, 31, v170
	v_or_b32_e32 v182, 16, v170
	v_lshl_add_u64 v[172:173], s[16:17], 0, v[202:203]
	v_lshlrev_b64 v[206:207], 11, v[170:171]
	v_ashrrev_i32_e32 v183, 31, v182
	v_or_b32_e32 v178, 32, v170
	v_lshl_add_u64 v[128:129], v[172:173], 0, v[206:207]
	v_lshlrev_b64 v[184:185], 11, v[182:183]
	v_ashrrev_i32_e32 v179, 31, v178
	v_or_b32_e32 v174, 48, v170
	global_load_dwordx4 v[194:197], v[128:129], off
	global_load_dwordx4 v[198:201], v[128:129], off offset:256
	v_lshl_add_u64 v[128:129], v[172:173], 0, v[184:185]
	v_lshlrev_b64 v[180:181], 11, v[178:179]
	v_ashrrev_i32_e32 v175, 31, v174
	global_load_dwordx4 v[148:151], v[128:129], off
	global_load_dwordx4 v[144:147], v[128:129], off offset:256
	v_lshl_add_u64 v[128:129], v[172:173], 0, v[180:181]
	v_lshlrev_b64 v[176:177], 11, v[174:175]
	global_load_dwordx4 v[140:143], v[128:129], off
	global_load_dwordx4 v[136:139], v[128:129], off offset:256
	v_lshl_add_u64 v[128:129], v[172:173], 0, v[176:177]
	global_load_dwordx4 v[132:135], v[128:129], off
	s_nop 0
	global_load_dwordx4 v[128:131], v[128:129], off offset:256
	v_and_b32_e32 v193, 64, v205
	v_xor_b32_e32 v192, 16, v205
	v_add_u32_e32 v208, 64, v193
	v_cmp_lt_i32_e32 vcc, v192, v208
	s_nop 1
	v_cndmask_b32_e32 v192, v205, v192, vcc
	v_lshlrev_b32_e32 v193, 2, v192
	v_xor_b32_e32 v192, 32, v205
	v_cmp_lt_i32_e32 vcc, v192, v208
	s_nop 1
	v_cndmask_b32_e32 v192, v205, v192, vcc
	v_lshlrev_b32_e32 v192, 2, v192
	v_add_u32_e32 v236, 0x80, v170
	v_ashrrev_i32_e32 v237, 31, v236
	v_lshlrev_b64 v[236:237], 11, v[236:237]
	v_lshl_add_u64 v[236:237], v[172:173], 0, v[236:237]
	global_load_dwordx4 v[224:227], v[236:237], off
	global_load_dwordx4 v[228:231], v[236:237], off offset:256
	v_add_u32_e32 v236, 0x90, v170
	v_ashrrev_i32_e32 v237, 31, v236
	v_lshlrev_b64 v[236:237], 11, v[236:237]
	v_lshl_add_u64 v[236:237], v[172:173], 0, v[236:237]
	global_load_dwordx4 v[232:235], v[236:237], off
	global_load_dwordx4 v[240:243], v[236:237], off offset:256
	v_add_u32_e32 v236, 0xa0, v170
	v_ashrrev_i32_e32 v237, 31, v236
	v_lshlrev_b64 v[236:237], 11, v[236:237]
	v_lshl_add_u64 v[236:237], v[172:173], 0, v[236:237]
	global_load_dwordx4 v[244:247], v[236:237], off
	global_load_dwordx4 v[248:251], v[236:237], off offset:256
	v_add_u32_e32 v236, 0xb0, v170
	v_ashrrev_i32_e32 v237, 31, v236
	v_lshlrev_b64 v[236:237], 11, v[236:237]
	v_lshl_add_u64 v[236:237], v[172:173], 0, v[236:237]
	global_load_dwordx4 v[252:255], v[236:237], off
	s_waitcnt vmcnt(0)
	v_lshlrev_b32_e32 v208, 16, v194
	v_and_b32_e32 v209, 0xffff0000, v194
	v_lshlrev_b32_e32 v194, 16, v195
	v_and_b32_e32 v195, 0xffff0000, v195
	v_lshlrev_b32_e32 v210, 16, v196
	v_and_b32_e32 v211, 0xffff0000, v196
	v_lshlrev_b32_e32 v196, 16, v197
	v_and_b32_e32 v197, 0xffff0000, v197
	v_pk_add_f32 v[126:127], v[126:127], v[194:195]
	v_pk_add_f32 v[194:195], v[122:123], v[196:197]
	v_pk_add_f32 v[196:197], v[120:121], v[210:211]
	v_pk_add_f32 v[124:125], v[124:125], v[208:209]
	v_cvt_pk_bf16_f32 v122, v196, v197
	v_mul_f32_e32 v196, v196, v196
	v_cvt_pk_bf16_f32 v120, v124, v125
	v_fmac_f32_e32 v196, v124, v124
	v_mul_f32_e32 v124, v197, v197
	v_fmac_f32_e32 v124, v125, v125
	v_mul_f32_e32 v125, v194, v194
	v_add_f32_e32 v124, v196, v124
	v_fmac_f32_e32 v125, v126, v126
	v_add_f32_e32 v124, v125, v124
	v_mul_f32_e32 v125, v195, v195
	v_cvt_pk_bf16_f32 v121, v126, v127
	v_cvt_pk_bf16_f32 v123, v194, v195
	v_fmac_f32_e32 v125, v127, v127
	v_lshlrev_b32_e32 v126, 16, v199
	v_and_b32_e32 v127, 0xffff0000, v199
	v_lshlrev_b32_e32 v194, 16, v200
	v_and_b32_e32 v195, 0xffff0000, v200
	v_add_f32_e32 v208, v125, v124
	v_lshlrev_b32_e32 v124, 16, v198
	v_and_b32_e32 v125, 0xffff0000, v198
	v_pk_add_f32 v[118:119], v[118:119], v[126:127]
	v_pk_add_f32 v[126:127], v[112:113], v[194:195]
	v_pk_add_f32 v[116:117], v[116:117], v[124:125]
	v_mul_f32_e32 v112, v126, v126
	v_lshlrev_b32_e32 v196, 16, v201
	v_and_b32_e32 v197, 0xffff0000, v201
	v_fmac_f32_e32 v112, v116, v116
	v_mul_f32_e32 v113, v127, v127
	v_pk_add_f32 v[124:125], v[114:115], v[196:197]
	v_add_f32_e32 v112, v112, v208
	v_fmac_f32_e32 v113, v117, v117
	v_add_f32_e32 v112, v113, v112
	v_mul_f32_e32 v113, v124, v124
	v_fmac_f32_e32 v113, v118, v118
	v_add_f32_e32 v112, v113, v112
	v_mul_f32_e32 v113, v125, v125
	v_fmac_f32_e32 v113, v119, v119
	v_add_f32_e32 v115, v113, v112
	ds_bpermute_b32 v196, v193, v115
	v_lshl_add_u64 v[112:113], s[16:17], 0, v[206:207]
	v_lshl_add_u64 v[194:195], v[112:113], 0, v[202:203]
	v_cvt_pk_bf16_f32 v114, v116, v117
	v_cvt_pk_bf16_f32 v116, v126, v127
	s_waitcnt lgkmcnt(0)
	v_add_f32_e32 v112, v115, v196
	ds_bpermute_b32 v113, v192, v112
	v_cvt_pk_bf16_f32 v115, v118, v119
	v_cvt_pk_bf16_f32 v117, v124, v125
	global_store_dwordx4 v[194:195], v[120:123], off
	global_store_dwordx4 v[194:195], v[114:117], off offset:256
	s_and_saveexec_b64 s[36:37], s[8:9]
	s_cbranch_execz .LBB0_1897
	s_waitcnt lgkmcnt(0)
	v_add_f32_e32 v112, v112, v113
	v_mul_f32_e32 v112, 0x4b800000, v112
	v_trunc_f32_e32 v112, v112
	v_mul_f32_e32 v113, 0x2f800000, v112
	v_floor_f32_e32 v113, v113
	v_fmac_f32_e32 v112, 0xcf800000, v113
	v_cvt_u32_f32_e32 v112, v112
	v_cvt_u32_f32_e32 v113, v113
	v_lshl_add_u64 v[114:115], v[170:171], 3, s[18:19]
	global_atomic_add_x2 v[114:115], v[112:113], off

.LBB0_1903:
	s_or_b64 exec, exec, s[36:37]
	v_add_u32_e32 v100, 0x80, v170
	v_ashrrev_i32_e32 v101, 31, v100
	v_add_u32_e32 v96, 0x90, v170
	v_lshlrev_b64 v[110:111], 11, v[100:101]
	v_ashrrev_i32_e32 v97, 31, v96
	v_add_u32_e32 v92, 0xa0, v170
	s_waitcnt lgkmcnt(0)
	v_lshl_add_u64 v[64:65], v[172:173], 0, v[110:111]
	v_lshlrev_b64 v[98:99], 11, v[96:97]
	v_ashrrev_i32_e32 v93, 31, v92
	v_add_u32_e32 v88, 0xb0, v170
	v_mov_b32_e32 v102, v224
	v_mov_b32_e32 v103, v225
	v_mov_b32_e32 v104, v226
	v_mov_b32_e32 v105, v227
	v_mov_b32_e32 v106, v228
	v_mov_b32_e32 v107, v229
	v_mov_b32_e32 v108, v230
	v_mov_b32_e32 v109, v231
	v_lshl_add_u64 v[64:65], v[172:173], 0, v[98:99]
	v_lshlrev_b64 v[94:95], 11, v[92:93]
	v_ashrrev_i32_e32 v89, 31, v88
	v_mov_b32_e32 v84, v232
	v_mov_b32_e32 v85, v233
	v_mov_b32_e32 v86, v234
	v_mov_b32_e32 v87, v235
	v_mov_b32_e32 v80, v240
	v_mov_b32_e32 v81, v241
	v_mov_b32_e32 v82, v242
	v_mov_b32_e32 v83, v243
	v_lshl_add_u64 v[64:65], v[172:173], 0, v[94:95]
	v_lshlrev_b64 v[90:91], 11, v[88:89]
	v_mov_b32_e32 v76, v244
	v_mov_b32_e32 v77, v245
	v_mov_b32_e32 v78, v246
	v_mov_b32_e32 v79, v247
	v_mov_b32_e32 v72, v248
	v_mov_b32_e32 v73, v249
	v_mov_b32_e32 v74, v250
	v_mov_b32_e32 v75, v251
	v_lshl_add_u64 v[64:65], v[172:173], 0, v[90:91]
	v_mov_b32_e32 v68, v252
	v_mov_b32_e32 v69, v253
	v_mov_b32_e32 v70, v254
	v_mov_b32_e32 v71, v255
	s_nop 0
	global_load_dwordx4 v[64:67], v[64:65], off offset:256
	s_waitcnt vmcnt(7)
	v_lshlrev_b32_e32 v112, 16, v102
	v_and_b32_e32 v113, 0xffff0000, v102
	v_lshlrev_b32_e32 v102, 16, v103
	v_and_b32_e32 v103, 0xffff0000, v103
	v_lshlrev_b32_e32 v114, 16, v104
	v_and_b32_e32 v115, 0xffff0000, v104
	v_lshlrev_b32_e32 v104, 16, v105
	v_and_b32_e32 v105, 0xffff0000, v105
	v_pk_add_f32 v[62:63], v[62:63], v[102:103]
	v_pk_add_f32 v[102:103], v[58:59], v[104:105]
	v_pk_add_f32 v[104:105], v[56:57], v[114:115]
	v_pk_add_f32 v[60:61], v[60:61], v[112:113]
	v_cvt_pk_bf16_f32 v58, v104, v105
	v_mul_f32_e32 v104, v104, v104
	v_cvt_pk_bf16_f32 v56, v60, v61
	v_fmac_f32_e32 v104, v60, v60
	v_mul_f32_e32 v60, v105, v105
	v_fmac_f32_e32 v60, v61, v61
	v_mul_f32_e32 v61, v102, v102
	v_add_f32_e32 v60, v104, v60
	v_fmac_f32_e32 v61, v62, v62
	v_add_f32_e32 v60, v61, v60
	v_mul_f32_e32 v61, v103, v103
	v_cvt_pk_bf16_f32 v57, v62, v63
	v_cvt_pk_bf16_f32 v59, v102, v103
	v_fmac_f32_e32 v61, v63, v63
	s_waitcnt vmcnt(6)
	v_lshlrev_b32_e32 v62, 16, v107
	v_and_b32_e32 v63, 0xffff0000, v107
	v_lshlrev_b32_e32 v102, 16, v108
	v_and_b32_e32 v103, 0xffff0000, v108
	v_add_f32_e32 v112, v61, v60
	v_lshlrev_b32_e32 v60, 16, v106
	v_and_b32_e32 v61, 0xffff0000, v106
	v_pk_add_f32 v[54:55], v[54:55], v[62:63]
	v_pk_add_f32 v[62:63], v[48:49], v[102:103]
	v_pk_add_f32 v[52:53], v[52:53], v[60:61]
	v_mul_f32_e32 v48, v62, v62
	v_lshlrev_b32_e32 v104, 16, v109
	v_and_b32_e32 v105, 0xffff0000, v109
	v_fmac_f32_e32 v48, v52, v52
	v_mul_f32_e32 v49, v63, v63
	v_pk_add_f32 v[60:61], v[50:51], v[104:105]
	v_add_f32_e32 v48, v48, v112
	v_fmac_f32_e32 v49, v53, v53
	v_add_f32_e32 v48, v49, v48
	v_mul_f32_e32 v49, v60, v60
	v_fmac_f32_e32 v49, v54, v54
	v_add_f32_e32 v48, v49, v48
	v_mul_f32_e32 v49, v61, v61
	v_fmac_f32_e32 v49, v55, v55
	v_add_f32_e32 v51, v49, v48
	ds_bpermute_b32 v104, v193, v51
	v_lshl_add_u64 v[48:49], s[16:17], 0, v[110:111]
	v_lshl_add_u64 v[102:103], v[168:169], 1, v[48:49]
	v_cvt_pk_bf16_f32 v50, v52, v53
	v_cvt_pk_bf16_f32 v52, v62, v63
	s_waitcnt lgkmcnt(0)
	v_add_f32_e32 v48, v51, v104
	ds_bpermute_b32 v49, v192, v48
	v_cvt_pk_bf16_f32 v51, v54, v55
	v_cvt_pk_bf16_f32 v53, v60, v61
	global_store_dwordx4 v[102:103], v[56:59], off
	global_store_dwordx4 v[102:103], v[50:53], off offset:256
	s_and_saveexec_b64 s[36:37], s[8:9]
	s_cbranch_execz .LBB0_1905
	s_waitcnt lgkmcnt(0)
	v_add_f32_e32 v48, v48, v49
	v_mul_f32_e32 v48, 0x4b800000, v48
	v_trunc_f32_e32 v48, v48
	v_mul_f32_e32 v49, 0x2f800000, v48
	v_floor_f32_e32 v49, v49
	v_fmac_f32_e32 v48, 0xcf800000, v49
	v_cvt_u32_f32_e32 v48, v48
	v_cvt_u32_f32_e32 v49, v49
	v_lshl_add_u64 v[50:51], v[100:101], 3, s[18:19]
	global_atomic_add_x2 v[50:51], v[48:49], off

.LBB0_2056:
	ds_read_b128 v[128:131], v189
	ds_read_b128 v[132:135], v189 offset:1024
	ds_read_b128 v[136:139], v189 offset:2048
	ds_read_b128 v[140:143], v189 offset:3072
	s_add_u32 s36, s34, 0xfff00080
	s_addc_u32 s37, s35, -1
	s_cmp_eq_u32 s53, 60
	s_cselect_b32 s39, s19, s37
	s_cselect_b32 s38, s29, s36
	s_cselect_b32 s37, s17, s52
	s_cselect_b32 s36, s50, s51
	v_lshl_add_u64 v[184:185], s[34:35], 0, v[160:161]
	s_add_i32 m0, s31, 0xc000
	ds_read_b128 v[144:147], v190
	ds_read_b128 v[148:151], v190 offset:1024
	ds_read_b128 v[168:171], v190 offset:2048
	ds_read_b128 v[172:175], v190 offset:3072
	ds_read_b128 v[176:179], v190 offset:4096
	ds_read_b128 v[180:183], v190 offset:5120
	ds_read_b128 v[192:195], v190 offset:6144
	ds_read_b128 v[196:199], v190 offset:7168
	global_load_lds_dwordx4 v[184:185], off
	v_lshl_add_u64 v[184:185], s[34:35], 0, v[162:163]
	s_add_i32 m0, s31, 0xe000
	s_nop 0
	global_load_lds_dwordx4 v[184:185], off
	s_waitcnt lgkmcnt(8)
	s_barrier
	s_waitcnt lgkmcnt(0)
	s_setprio 1
	s_waitcnt lgkmcnt(0)
	v_mfma_f32_16x16x32_bf16 v[124:127], v[128:131], v[144:147], v[124:127]
	v_mfma_f32_16x16x32_bf16 v[120:123], v[136:139], v[144:147], v[120:123]
	v_mfma_f32_16x16x32_bf16 v[108:111], v[128:131], v[168:171], v[108:111]
	v_mfma_f32_16x16x32_bf16 v[104:107], v[136:139], v[168:171], v[104:107]
	v_mfma_f32_16x16x32_bf16 v[92:95], v[128:131], v[176:179], v[92:95]
	v_mfma_f32_16x16x32_bf16 v[88:91], v[136:139], v[176:179], v[88:91]
	v_mfma_f32_16x16x32_bf16 v[76:79], v[128:131], v[192:195], v[76:79]
	v_mfma_f32_16x16x32_bf16 v[72:75], v[136:139], v[192:195], v[72:75]
	v_mfma_f32_16x16x32_bf16 v[124:127], v[132:135], v[148:151], v[124:127]
	v_mfma_f32_16x16x32_bf16 v[120:123], v[140:143], v[148:151], v[120:123]
	v_mfma_f32_16x16x32_bf16 v[108:111], v[132:135], v[172:175], v[108:111]
	v_mfma_f32_16x16x32_bf16 v[104:107], v[140:143], v[172:175], v[104:107]
	v_mfma_f32_16x16x32_bf16 v[92:95], v[132:135], v[180:183], v[92:95]
	v_mfma_f32_16x16x32_bf16 v[88:91], v[140:143], v[180:183], v[88:91]
	v_mfma_f32_16x16x32_bf16 v[76:79], v[132:135], v[196:199], v[76:79]
	v_mfma_f32_16x16x32_bf16 v[72:75], v[140:143], v[196:199], v[72:75]
	s_setprio 0
	s_barrier
	s_add_i32 s54, s48, s21
	v_lshl_add_u64 v[184:185], s[36:37], 0, v[154:155]
	s_mov_b32 m0, s54
	ds_read_b128 v[200:203], v191
	ds_read_b128 v[206:209], v191 offset:1024
	ds_read_b128 v[210:213], v191 offset:2048
	ds_read_b128 v[214:217], v191 offset:3072
	global_load_lds_dwordx4 v[184:185], off
	v_lshl_add_u64 v[218:219], s[36:37], 0, v[158:159]
	s_add_i32 m0, s54, 0x2000
	s_nop 0
	global_load_lds_dwordx4 v[218:219], off
	s_barrier
	s_waitcnt lgkmcnt(0)
	s_setprio 1
	s_waitcnt lgkmcnt(0)
	v_mfma_f32_16x16x32_bf16 v[116:119], v[200:203], v[144:147], v[116:119]
	v_mfma_f32_16x16x32_bf16 v[112:115], v[210:213], v[144:147], v[112:115]
	v_mfma_f32_16x16x32_bf16 v[100:103], v[200:203], v[168:171], v[100:103]
	v_mfma_f32_16x16x32_bf16 v[96:99], v[210:213], v[168:171], v[96:99]
	v_mfma_f32_16x16x32_bf16 v[84:87], v[200:203], v[176:179], v[84:87]
	v_mfma_f32_16x16x32_bf16 v[80:83], v[210:213], v[176:179], v[80:83]
	v_mfma_f32_16x16x32_bf16 v[68:71], v[200:203], v[192:195], v[68:71]
	v_mfma_f32_16x16x32_bf16 v[64:67], v[210:213], v[192:195], v[64:67]
	v_mfma_f32_16x16x32_bf16 v[116:119], v[206:209], v[148:151], v[116:119]
	v_mfma_f32_16x16x32_bf16 v[112:115], v[214:217], v[148:151], v[112:115]
	v_mfma_f32_16x16x32_bf16 v[100:103], v[206:209], v[172:175], v[100:103]
	v_mfma_f32_16x16x32_bf16 v[96:99], v[214:217], v[172:175], v[96:99]
	v_mfma_f32_16x16x32_bf16 v[84:87], v[206:209], v[180:183], v[84:87]
	v_mfma_f32_16x16x32_bf16 v[80:83], v[214:217], v[180:183], v[80:83]
	v_mfma_f32_16x16x32_bf16 v[68:71], v[206:209], v[196:199], v[68:71]
	v_mfma_f32_16x16x32_bf16 v[64:67], v[214:217], v[196:199], v[64:67]
	s_setprio 0
	s_mov_b32 m0, s31
	v_lshl_add_u64 v[220:221], s[38:39], 0, v[152:153]
	s_barrier
	ds_read_b128 v[144:147], v190 offset:16384
	ds_read_b128 v[148:151], v190 offset:17408
	ds_read_b128 v[168:171], v190 offset:18432
	ds_read_b128 v[172:175], v190 offset:19456
	ds_read_b128 v[176:179], v190 offset:20480
	ds_read_b128 v[180:183], v190 offset:21504
	ds_read_b128 v[192:195], v190 offset:22528
	ds_read_b128 v[196:199], v190 offset:23552
	global_load_lds_dwordx4 v[220:221], off
	v_lshl_add_u64 v[222:223], s[38:39], 0, v[156:157]
	s_mov_b32 m0, s33
	s_nop 0
	global_load_lds_dwordx4 v[222:223], off
	s_barrier
	s_waitcnt lgkmcnt(0)
	s_setprio 1
	s_waitcnt lgkmcnt(0)
	v_mfma_f32_16x16x32_bf16 v[60:63], v[128:131], v[144:147], v[60:63]
	v_mfma_f32_16x16x32_bf16 v[56:59], v[136:139], v[144:147], v[56:59]
	v_mfma_f32_16x16x32_bf16 v[44:47], v[128:131], v[168:171], v[44:47]
	v_mfma_f32_16x16x32_bf16 v[40:43], v[136:139], v[168:171], v[40:43]
	v_mfma_f32_16x16x32_bf16 v[28:31], v[128:131], v[176:179], v[28:31]
	v_mfma_f32_16x16x32_bf16 v[24:27], v[136:139], v[176:179], v[24:27]
	v_mfma_f32_16x16x32_bf16 v[12:15], v[128:131], v[192:195], v[12:15]
	v_mfma_f32_16x16x32_bf16 v[8:11], v[136:139], v[192:195], v[8:11]
	v_mfma_f32_16x16x32_bf16 v[60:63], v[132:135], v[148:151], v[60:63]
	v_mfma_f32_16x16x32_bf16 v[56:59], v[140:143], v[148:151], v[56:59]
	v_mfma_f32_16x16x32_bf16 v[44:47], v[132:135], v[172:175], v[44:47]
	v_mfma_f32_16x16x32_bf16 v[40:43], v[140:143], v[172:175], v[40:43]
	v_mfma_f32_16x16x32_bf16 v[28:31], v[132:135], v[180:183], v[28:31]
	v_mfma_f32_16x16x32_bf16 v[24:27], v[140:143], v[180:183], v[24:27]
	v_mfma_f32_16x16x32_bf16 v[12:15], v[132:135], v[196:199], v[12:15]
	v_mfma_f32_16x16x32_bf16 v[8:11], v[140:143], v[196:199], v[8:11]
	s_setprio 0
	s_barrier
	s_add_u32 s54, s36, 0x100000
	s_addc_u32 s55, s37, 0
	s_add_i32 s56, s49, s21
	v_lshl_add_u64 v[128:129], s[54:55], 0, v[154:155]
	s_mov_b32 m0, s56
	s_nop 0
	global_load_lds_dwordx4 v[128:129], off
	v_lshl_add_u64 v[128:129], s[54:55], 0, v[158:159]
	s_add_i32 m0, s56, 0x2000
	s_nop 0
	global_load_lds_dwordx4 v[128:129], off
	s_waitcnt vmcnt(6)
	s_barrier
	s_setprio 1
	v_mfma_f32_16x16x32_bf16 v[52:55], v[200:203], v[144:147], v[52:55]
	v_mfma_f32_16x16x32_bf16 v[48:51], v[210:213], v[144:147], v[48:51]
	v_mfma_f32_16x16x32_bf16 v[36:39], v[200:203], v[168:171], v[36:39]
	v_mfma_f32_16x16x32_bf16 v[32:35], v[210:213], v[168:171], v[32:35]
	v_mfma_f32_16x16x32_bf16 v[20:23], v[200:203], v[176:179], v[20:23]
	v_mfma_f32_16x16x32_bf16 v[16:19], v[210:213], v[176:179], v[16:19]
	v_mfma_f32_16x16x32_bf16 v[4:7], v[200:203], v[192:195], v[4:7]
	v_mfma_f32_16x16x32_bf16 v[0:3], v[210:213], v[192:195], v[0:3]
	v_mfma_f32_16x16x32_bf16 v[52:55], v[206:209], v[148:151], v[52:55]
	v_mfma_f32_16x16x32_bf16 v[48:51], v[214:217], v[148:151], v[48:51]
	v_mfma_f32_16x16x32_bf16 v[36:39], v[206:209], v[172:175], v[36:39]
	v_mfma_f32_16x16x32_bf16 v[32:35], v[214:217], v[172:175], v[32:35]
	v_mfma_f32_16x16x32_bf16 v[20:23], v[206:209], v[180:183], v[20:23]
	v_mfma_f32_16x16x32_bf16 v[16:19], v[214:217], v[180:183], v[16:19]
	v_mfma_f32_16x16x32_bf16 v[4:7], v[206:209], v[196:199], v[4:7]
	v_mfma_f32_16x16x32_bf16 v[0:3], v[214:217], v[196:199], v[0:3]
	s_setprio 0
	s_add_i32 s54, 0, 0x18000
	v_add_u32_e32 v140, s54, v187
	s_barrier
	ds_read_b128 v[128:131], v140
	ds_read_b128 v[132:135], v140 offset:1024
	ds_read_b128 v[136:139], v140 offset:2048
	ds_read_b128 v[140:143], v140 offset:3072
	s_add_u32 s38, s38, 0x100000
	s_addc_u32 s39, s39, 0
	s_mov_b32 m0, s40
	v_lshl_add_u64 v[200:201], s[38:39], 0, v[152:153]
	ds_read_b128 v[144:147], v190 offset:32768
	ds_read_b128 v[148:151], v190 offset:33792
	ds_read_b128 v[168:171], v190 offset:34816
	ds_read_b128 v[172:175], v190 offset:35840
	ds_read_b128 v[176:179], v190 offset:36864
	ds_read_b128 v[180:183], v190 offset:37888
	ds_read_b128 v[192:195], v190 offset:38912
	ds_read_b128 v[196:199], v190 offset:39936
	global_load_lds_dwordx4 v[200:201], off
	v_lshl_add_u64 v[200:201], s[38:39], 0, v[156:157]
	s_mov_b32 m0, s41
	s_nop 0
	global_load_lds_dwordx4 v[200:201], off
	s_waitcnt lgkmcnt(8)
	s_barrier
	s_waitcnt lgkmcnt(0)
	s_setprio 1
	s_waitcnt lgkmcnt(0)
	v_mfma_f32_16x16x32_bf16 v[124:127], v[128:131], v[144:147], v[124:127]
	v_mfma_f32_16x16x32_bf16 v[120:123], v[136:139], v[144:147], v[120:123]
	v_mfma_f32_16x16x32_bf16 v[108:111], v[128:131], v[168:171], v[108:111]
	v_mfma_f32_16x16x32_bf16 v[104:107], v[136:139], v[168:171], v[104:107]
	v_mfma_f32_16x16x32_bf16 v[92:95], v[128:131], v[176:179], v[92:95]
	v_mfma_f32_16x16x32_bf16 v[88:91], v[136:139], v[176:179], v[88:91]
	v_mfma_f32_16x16x32_bf16 v[76:79], v[128:131], v[192:195], v[76:79]
	v_mfma_f32_16x16x32_bf16 v[72:75], v[136:139], v[192:195], v[72:75]
	v_mfma_f32_16x16x32_bf16 v[124:127], v[132:135], v[148:151], v[124:127]
	v_mfma_f32_16x16x32_bf16 v[120:123], v[140:143], v[148:151], v[120:123]
	v_mfma_f32_16x16x32_bf16 v[108:111], v[132:135], v[172:175], v[108:111]
	v_mfma_f32_16x16x32_bf16 v[104:107], v[140:143], v[172:175], v[104:107]
	v_mfma_f32_16x16x32_bf16 v[92:95], v[132:135], v[180:183], v[92:95]
	v_mfma_f32_16x16x32_bf16 v[88:91], v[140:143], v[180:183], v[88:91]
	v_mfma_f32_16x16x32_bf16 v[76:79], v[132:135], v[196:199], v[76:79]
	v_mfma_f32_16x16x32_bf16 v[72:75], v[140:143], v[196:199], v[72:75]
	s_setprio 0
	s_barrier
	s_add_i32 s38, 0, 0x1c000
	s_add_i32 s39, s54, s21
	v_add_u32_e32 v214, s38, v187
	v_lshl_add_u64 v[184:185], v[184:185], 0, s[14:15]
	s_mov_b32 m0, s39
	ds_read_b128 v[200:203], v214
	ds_read_b128 v[206:209], v214 offset:1024
	ds_read_b128 v[210:213], v214 offset:2048
	ds_read_b128 v[214:217], v214 offset:3072
	global_load_lds_dwordx4 v[184:185], off
	v_lshl_add_u64 v[184:185], v[218:219], 0, s[14:15]
	s_add_i32 m0, s39, 0x2000
	s_nop 0
	global_load_lds_dwordx4 v[184:185], off
	s_barrier
	s_waitcnt lgkmcnt(0)
	s_setprio 1
	s_waitcnt lgkmcnt(0)
	v_mfma_f32_16x16x32_bf16 v[116:119], v[200:203], v[144:147], v[116:119]
	v_mfma_f32_16x16x32_bf16 v[112:115], v[210:213], v[144:147], v[112:115]
	v_mfma_f32_16x16x32_bf16 v[100:103], v[200:203], v[168:171], v[100:103]
	v_mfma_f32_16x16x32_bf16 v[96:99], v[210:213], v[168:171], v[96:99]
	v_mfma_f32_16x16x32_bf16 v[84:87], v[200:203], v[176:179], v[84:87]
	v_mfma_f32_16x16x32_bf16 v[80:83], v[210:213], v[176:179], v[80:83]
	v_mfma_f32_16x16x32_bf16 v[68:71], v[200:203], v[192:195], v[68:71]
	v_mfma_f32_16x16x32_bf16 v[64:67], v[210:213], v[192:195], v[64:67]
	v_mfma_f32_16x16x32_bf16 v[116:119], v[206:209], v[148:151], v[116:119]
	v_mfma_f32_16x16x32_bf16 v[112:115], v[214:217], v[148:151], v[112:115]
	v_mfma_f32_16x16x32_bf16 v[100:103], v[206:209], v[172:175], v[100:103]
	v_mfma_f32_16x16x32_bf16 v[96:99], v[214:217], v[172:175], v[96:99]
	v_mfma_f32_16x16x32_bf16 v[84:87], v[206:209], v[180:183], v[84:87]
	v_mfma_f32_16x16x32_bf16 v[80:83], v[214:217], v[180:183], v[80:83]
	v_mfma_f32_16x16x32_bf16 v[68:71], v[206:209], v[196:199], v[68:71]
	v_mfma_f32_16x16x32_bf16 v[64:67], v[214:217], v[196:199], v[64:67]
	s_setprio 0
	s_mov_b32 m0, s43
	v_lshl_add_u64 v[184:185], v[220:221], 0, s[14:15]
	s_barrier
	ds_read_b128 v[144:147], v190 offset:49152
	ds_read_b128 v[148:151], v190 offset:50176
	ds_read_b128 v[168:171], v190 offset:51200
	ds_read_b128 v[172:175], v190 offset:52224
	ds_read_b128 v[176:179], v190 offset:53248
	ds_read_b128 v[180:183], v190 offset:54272
	ds_read_b128 v[192:195], v190 offset:55296
	ds_read_b128 v[196:199], v190 offset:56320
	global_load_lds_dwordx4 v[184:185], off
	v_lshl_add_u64 v[184:185], v[222:223], 0, s[14:15]
	s_mov_b32 m0, s44
	s_nop 0
	global_load_lds_dwordx4 v[184:185], off
	s_barrier
	s_waitcnt lgkmcnt(0)
	s_setprio 1
	s_waitcnt lgkmcnt(0)
	v_mfma_f32_16x16x32_bf16 v[60:63], v[128:131], v[144:147], v[60:63]
	v_mfma_f32_16x16x32_bf16 v[56:59], v[136:139], v[144:147], v[56:59]
	v_mfma_f32_16x16x32_bf16 v[44:47], v[128:131], v[168:171], v[44:47]
	v_mfma_f32_16x16x32_bf16 v[40:43], v[136:139], v[168:171], v[40:43]
	v_mfma_f32_16x16x32_bf16 v[28:31], v[128:131], v[176:179], v[28:31]
	v_mfma_f32_16x16x32_bf16 v[24:27], v[136:139], v[176:179], v[24:27]
	v_mfma_f32_16x16x32_bf16 v[12:15], v[128:131], v[192:195], v[12:15]
	v_mfma_f32_16x16x32_bf16 v[8:11], v[136:139], v[192:195], v[8:11]
	v_mfma_f32_16x16x32_bf16 v[60:63], v[132:135], v[148:151], v[60:63]
	v_mfma_f32_16x16x32_bf16 v[56:59], v[140:143], v[148:151], v[56:59]
	v_mfma_f32_16x16x32_bf16 v[44:47], v[132:135], v[172:175], v[44:47]
	v_mfma_f32_16x16x32_bf16 v[40:43], v[140:143], v[172:175], v[40:43]
	v_mfma_f32_16x16x32_bf16 v[28:31], v[132:135], v[180:183], v[28:31]
	v_mfma_f32_16x16x32_bf16 v[24:27], v[140:143], v[180:183], v[24:27]
	v_mfma_f32_16x16x32_bf16 v[12:15], v[132:135], v[196:199], v[12:15]
	v_mfma_f32_16x16x32_bf16 v[8:11], v[140:143], v[196:199], v[8:11]
	s_setprio 0
	s_barrier
	s_add_u32 s36, s36, 0x100080
	s_addc_u32 s37, s37, 0
	s_add_i32 s38, s38, s21
	v_lshl_add_u64 v[128:129], s[36:37], 0, v[154:155]
	s_mov_b32 m0, s38
	s_nop 0
	global_load_lds_dwordx4 v[128:129], off
	v_lshl_add_u64 v[128:129], s[36:37], 0, v[158:159]
	s_add_i32 m0, s38, 0x2000
	s_nop 0
	global_load_lds_dwordx4 v[128:129], off
	s_waitcnt vmcnt(6)
	s_barrier
	s_setprio 1
	v_mfma_f32_16x16x32_bf16 v[52:55], v[200:203], v[144:147], v[52:55]
	v_mfma_f32_16x16x32_bf16 v[48:51], v[210:213], v[144:147], v[48:51]
	v_mfma_f32_16x16x32_bf16 v[36:39], v[200:203], v[168:171], v[36:39]
	v_mfma_f32_16x16x32_bf16 v[32:35], v[210:213], v[168:171], v[32:35]
	v_mfma_f32_16x16x32_bf16 v[20:23], v[200:203], v[176:179], v[20:23]
	v_mfma_f32_16x16x32_bf16 v[16:19], v[210:213], v[176:179], v[16:19]
	v_mfma_f32_16x16x32_bf16 v[4:7], v[200:203], v[192:195], v[4:7]
	v_mfma_f32_16x16x32_bf16 v[0:3], v[210:213], v[192:195], v[0:3]
	v_mfma_f32_16x16x32_bf16 v[52:55], v[206:209], v[148:151], v[52:55]
	v_mfma_f32_16x16x32_bf16 v[48:51], v[214:217], v[148:151], v[48:51]
	v_mfma_f32_16x16x32_bf16 v[36:39], v[206:209], v[172:175], v[36:39]
	v_mfma_f32_16x16x32_bf16 v[32:35], v[214:217], v[172:175], v[32:35]
	v_mfma_f32_16x16x32_bf16 v[20:23], v[206:209], v[180:183], v[20:23]
	v_mfma_f32_16x16x32_bf16 v[16:19], v[214:217], v[180:183], v[16:19]
	v_mfma_f32_16x16x32_bf16 v[4:7], v[206:209], v[196:199], v[4:7]
	v_mfma_f32_16x16x32_bf16 v[0:3], v[214:217], v[196:199], v[0:3]
	s_setprio 0
	s_add_i32 s53, s53, 2
	s_add_u32 s34, s34, 0x100
	s_addc_u32 s35, s35, 0
	s_add_u32 s51, s51, 0x100
	s_addc_u32 s52, s52, 0
	s_cmp_gt_u32 s53, 61
	s_barrier
	s_cbranch_scc0 .LBB0_2056
	v_lshl_or_b32 v168, s30, 8, v188
	v_lshl_add_u32 v170, s28, 8, v186
	v_ashrrev_i32_e32 v169, 31, v168
	v_lshlrev_b64 v[202:203], 1, v[168:169]
	v_ashrrev_i32_e32 v171, 31, v170
	v_or_b32_e32 v182, 16, v170
	v_lshl_add_u64 v[172:173], s[10:11], 0, v[202:203]
	v_lshlrev_b64 v[206:207], 11, v[170:171]
	v_ashrrev_i32_e32 v183, 31, v182
	v_or_b32_e32 v178, 32, v170
	v_lshl_add_u64 v[128:129], v[172:173], 0, v[206:207]
	v_lshlrev_b64 v[184:185], 11, v[182:183]
	v_ashrrev_i32_e32 v179, 31, v178
	v_or_b32_e32 v174, 48, v170
	global_load_dwordx4 v[194:197], v[128:129], off
	global_load_dwordx4 v[198:201], v[128:129], off offset:256
	v_lshl_add_u64 v[128:129], v[172:173], 0, v[184:185]
	v_lshlrev_b64 v[180:181], 11, v[178:179]
	v_ashrrev_i32_e32 v175, 31, v174
	global_load_dwordx4 v[148:151], v[128:129], off
	global_load_dwordx4 v[144:147], v[128:129], off offset:256
	v_lshl_add_u64 v[128:129], v[172:173], 0, v[180:181]
	v_lshlrev_b64 v[176:177], 11, v[174:175]
	global_load_dwordx4 v[140:143], v[128:129], off
	global_load_dwordx4 v[136:139], v[128:129], off offset:256
	v_lshl_add_u64 v[128:129], v[172:173], 0, v[176:177]
	global_load_dwordx4 v[132:135], v[128:129], off
	s_nop 0
	global_load_dwordx4 v[128:131], v[128:129], off offset:256
	v_and_b32_e32 v193, 64, v205
	v_xor_b32_e32 v192, 16, v205
	v_add_u32_e32 v208, 64, v193
	v_cmp_lt_i32_e32 vcc, v192, v208
	s_nop 1
	v_cndmask_b32_e32 v192, v205, v192, vcc
	v_lshlrev_b32_e32 v193, 2, v192
	v_xor_b32_e32 v192, 32, v205
	v_cmp_lt_i32_e32 vcc, v192, v208
	s_nop 1
	v_cndmask_b32_e32 v192, v205, v192, vcc
	v_lshlrev_b32_e32 v192, 2, v192
	v_add_u32_e32 v236, 0x80, v170
	v_ashrrev_i32_e32 v237, 31, v236
	v_lshlrev_b64 v[236:237], 11, v[236:237]
	v_lshl_add_u64 v[236:237], v[172:173], 0, v[236:237]
	global_load_dwordx4 v[224:227], v[236:237], off
	global_load_dwordx4 v[228:231], v[236:237], off offset:256
	v_add_u32_e32 v236, 0x90, v170
	v_ashrrev_i32_e32 v237, 31, v236
	v_lshlrev_b64 v[236:237], 11, v[236:237]
	v_lshl_add_u64 v[236:237], v[172:173], 0, v[236:237]
	global_load_dwordx4 v[232:235], v[236:237], off
	global_load_dwordx4 v[240:243], v[236:237], off offset:256
	v_add_u32_e32 v236, 0xa0, v170
	v_ashrrev_i32_e32 v237, 31, v236
	v_lshlrev_b64 v[236:237], 11, v[236:237]
	v_lshl_add_u64 v[236:237], v[172:173], 0, v[236:237]
	global_load_dwordx4 v[244:247], v[236:237], off
	global_load_dwordx4 v[248:251], v[236:237], off offset:256
	v_add_u32_e32 v236, 0xb0, v170
	v_ashrrev_i32_e32 v237, 31, v236
	v_lshlrev_b64 v[236:237], 11, v[236:237]
	v_lshl_add_u64 v[236:237], v[172:173], 0, v[236:237]
	global_load_dwordx4 v[252:255], v[236:237], off
	s_waitcnt vmcnt(0)
	v_lshlrev_b32_e32 v208, 16, v194
	v_and_b32_e32 v209, 0xffff0000, v194
	v_lshlrev_b32_e32 v194, 16, v195
	v_and_b32_e32 v195, 0xffff0000, v195
	v_lshlrev_b32_e32 v210, 16, v196
	v_and_b32_e32 v211, 0xffff0000, v196
	v_lshlrev_b32_e32 v196, 16, v197
	v_and_b32_e32 v197, 0xffff0000, v197
	v_pk_add_f32 v[126:127], v[126:127], v[194:195]
	v_pk_add_f32 v[194:195], v[122:123], v[196:197]
	v_pk_add_f32 v[196:197], v[120:121], v[210:211]
	v_pk_add_f32 v[124:125], v[124:125], v[208:209]
	v_cvt_pk_bf16_f32 v122, v196, v197
	v_mul_f32_e32 v196, v196, v196
	v_cvt_pk_bf16_f32 v120, v124, v125
	v_fmac_f32_e32 v196, v124, v124
	v_mul_f32_e32 v124, v197, v197
	v_fmac_f32_e32 v124, v125, v125
	v_mul_f32_e32 v125, v194, v194
	v_add_f32_e32 v124, v196, v124
	v_fmac_f32_e32 v125, v126, v126
	v_add_f32_e32 v124, v125, v124
	v_mul_f32_e32 v125, v195, v195
	v_cvt_pk_bf16_f32 v121, v126, v127
	v_cvt_pk_bf16_f32 v123, v194, v195
	v_fmac_f32_e32 v125, v127, v127
	v_lshlrev_b32_e32 v126, 16, v199
	v_and_b32_e32 v127, 0xffff0000, v199
	v_lshlrev_b32_e32 v194, 16, v200
	v_and_b32_e32 v195, 0xffff0000, v200
	v_add_f32_e32 v208, v125, v124
	v_lshlrev_b32_e32 v124, 16, v198
	v_and_b32_e32 v125, 0xffff0000, v198
	v_pk_add_f32 v[118:119], v[118:119], v[126:127]
	v_pk_add_f32 v[126:127], v[112:113], v[194:195]
	v_pk_add_f32 v[116:117], v[116:117], v[124:125]
	v_mul_f32_e32 v112, v126, v126
	v_lshlrev_b32_e32 v196, 16, v201
	v_and_b32_e32 v197, 0xffff0000, v201
	v_fmac_f32_e32 v112, v116, v116
	v_mul_f32_e32 v113, v127, v127
	v_pk_add_f32 v[124:125], v[114:115], v[196:197]
	v_add_f32_e32 v112, v112, v208
	v_fmac_f32_e32 v113, v117, v117
	v_add_f32_e32 v112, v113, v112
	v_mul_f32_e32 v113, v124, v124
	v_fmac_f32_e32 v113, v118, v118
	v_add_f32_e32 v112, v113, v112
	v_mul_f32_e32 v113, v125, v125
	v_fmac_f32_e32 v113, v119, v119
	v_add_f32_e32 v115, v113, v112
	ds_bpermute_b32 v196, v193, v115
	v_lshl_add_u64 v[112:113], s[10:11], 0, v[206:207]
	v_lshl_add_u64 v[194:195], v[112:113], 0, v[202:203]
	v_cvt_pk_bf16_f32 v114, v116, v117
	v_cvt_pk_bf16_f32 v116, v126, v127
	s_waitcnt lgkmcnt(0)
	v_add_f32_e32 v112, v115, v196
	ds_bpermute_b32 v113, v192, v112
	v_cvt_pk_bf16_f32 v115, v118, v119
	v_cvt_pk_bf16_f32 v117, v124, v125
	global_store_dwordx4 v[194:195], v[120:123], off
	global_store_dwordx4 v[194:195], v[114:117], off offset:256
	s_and_saveexec_b64 s[28:29], s[4:5]
	s_cbranch_execz .LBB0_2059
	s_waitcnt lgkmcnt(0)
	v_add_f32_e32 v112, v112, v113
	v_mul_f32_e32 v112, 0x4b800000, v112
	v_trunc_f32_e32 v112, v112
	v_mul_f32_e32 v113, 0x2f800000, v112
	v_floor_f32_e32 v113, v113
	v_fmac_f32_e32 v112, 0xcf800000, v113
	v_cvt_u32_f32_e32 v112, v112
	v_cvt_u32_f32_e32 v113, v113
	v_lshl_add_u64 v[114:115], v[170:171], 3, s[12:13]
	global_atomic_add_x2 v[114:115], v[112:113], off

.LBB0_2065:
	s_or_b64 exec, exec, s[28:29]
	v_add_u32_e32 v100, 0x80, v170
	v_ashrrev_i32_e32 v101, 31, v100
	v_add_u32_e32 v96, 0x90, v170
	v_lshlrev_b64 v[110:111], 11, v[100:101]
	v_ashrrev_i32_e32 v97, 31, v96
	v_add_u32_e32 v92, 0xa0, v170
	s_waitcnt lgkmcnt(0)
	v_lshl_add_u64 v[64:65], v[172:173], 0, v[110:111]
	v_lshlrev_b64 v[98:99], 11, v[96:97]
	v_ashrrev_i32_e32 v93, 31, v92
	v_add_u32_e32 v88, 0xb0, v170
	v_mov_b32_e32 v102, v224
	v_mov_b32_e32 v103, v225
	v_mov_b32_e32 v104, v226
	v_mov_b32_e32 v105, v227
	v_mov_b32_e32 v106, v228
	v_mov_b32_e32 v107, v229
	v_mov_b32_e32 v108, v230
	v_mov_b32_e32 v109, v231
	v_lshl_add_u64 v[64:65], v[172:173], 0, v[98:99]
	v_lshlrev_b64 v[94:95], 11, v[92:93]
	v_ashrrev_i32_e32 v89, 31, v88
	v_mov_b32_e32 v84, v232
	v_mov_b32_e32 v85, v233
	v_mov_b32_e32 v86, v234
	v_mov_b32_e32 v87, v235
	v_mov_b32_e32 v80, v240
	v_mov_b32_e32 v81, v241
	v_mov_b32_e32 v82, v242
	v_mov_b32_e32 v83, v243
	v_lshl_add_u64 v[64:65], v[172:173], 0, v[94:95]
	v_lshlrev_b64 v[90:91], 11, v[88:89]
	v_mov_b32_e32 v76, v244
	v_mov_b32_e32 v77, v245
	v_mov_b32_e32 v78, v246
	v_mov_b32_e32 v79, v247
	v_mov_b32_e32 v72, v248
	v_mov_b32_e32 v73, v249
	v_mov_b32_e32 v74, v250
	v_mov_b32_e32 v75, v251
	v_lshl_add_u64 v[64:65], v[172:173], 0, v[90:91]
	v_mov_b32_e32 v68, v252
	v_mov_b32_e32 v69, v253
	v_mov_b32_e32 v70, v254
	v_mov_b32_e32 v71, v255
	s_nop 0
	global_load_dwordx4 v[64:67], v[64:65], off offset:256
	s_waitcnt vmcnt(7)
	v_lshlrev_b32_e32 v112, 16, v102
	v_and_b32_e32 v113, 0xffff0000, v102
	v_lshlrev_b32_e32 v102, 16, v103
	v_and_b32_e32 v103, 0xffff0000, v103
	v_lshlrev_b32_e32 v114, 16, v104
	v_and_b32_e32 v115, 0xffff0000, v104
	v_lshlrev_b32_e32 v104, 16, v105
	v_and_b32_e32 v105, 0xffff0000, v105
	v_pk_add_f32 v[62:63], v[62:63], v[102:103]
	v_pk_add_f32 v[102:103], v[58:59], v[104:105]
	v_pk_add_f32 v[104:105], v[56:57], v[114:115]
	v_pk_add_f32 v[60:61], v[60:61], v[112:113]
	v_cvt_pk_bf16_f32 v58, v104, v105
	v_mul_f32_e32 v104, v104, v104
	v_cvt_pk_bf16_f32 v56, v60, v61
	v_fmac_f32_e32 v104, v60, v60
	v_mul_f32_e32 v60, v105, v105
	v_fmac_f32_e32 v60, v61, v61
	v_mul_f32_e32 v61, v102, v102
	v_add_f32_e32 v60, v104, v60
	v_fmac_f32_e32 v61, v62, v62
	v_add_f32_e32 v60, v61, v60
	v_mul_f32_e32 v61, v103, v103
	v_cvt_pk_bf16_f32 v57, v62, v63
	v_cvt_pk_bf16_f32 v59, v102, v103
	v_fmac_f32_e32 v61, v63, v63
	s_waitcnt vmcnt(6)
	v_lshlrev_b32_e32 v62, 16, v107
	v_and_b32_e32 v63, 0xffff0000, v107
	v_lshlrev_b32_e32 v102, 16, v108
	v_and_b32_e32 v103, 0xffff0000, v108
	v_add_f32_e32 v112, v61, v60
	v_lshlrev_b32_e32 v60, 16, v106
	v_and_b32_e32 v61, 0xffff0000, v106
	v_pk_add_f32 v[54:55], v[54:55], v[62:63]
	v_pk_add_f32 v[62:63], v[48:49], v[102:103]
	v_pk_add_f32 v[52:53], v[52:53], v[60:61]
	v_mul_f32_e32 v48, v62, v62
	v_lshlrev_b32_e32 v104, 16, v109
	v_and_b32_e32 v105, 0xffff0000, v109
	v_fmac_f32_e32 v48, v52, v52
	v_mul_f32_e32 v49, v63, v63
	v_pk_add_f32 v[60:61], v[50:51], v[104:105]
	v_add_f32_e32 v48, v48, v112
	v_fmac_f32_e32 v49, v53, v53
	v_add_f32_e32 v48, v49, v48
	v_mul_f32_e32 v49, v60, v60
	v_fmac_f32_e32 v49, v54, v54
	v_add_f32_e32 v48, v49, v48
	v_mul_f32_e32 v49, v61, v61
	v_fmac_f32_e32 v49, v55, v55
	v_add_f32_e32 v51, v49, v48
	ds_bpermute_b32 v104, v193, v51
	v_lshl_add_u64 v[48:49], s[10:11], 0, v[110:111]
	v_lshl_add_u64 v[102:103], v[168:169], 1, v[48:49]
	v_cvt_pk_bf16_f32 v50, v52, v53
	v_cvt_pk_bf16_f32 v52, v62, v63
	s_waitcnt lgkmcnt(0)
	v_add_f32_e32 v48, v51, v104
	ds_bpermute_b32 v49, v192, v48
	v_cvt_pk_bf16_f32 v51, v54, v55
	v_cvt_pk_bf16_f32 v53, v60, v61
	global_store_dwordx4 v[102:103], v[56:59], off
	global_store_dwordx4 v[102:103], v[50:53], off offset:256
	s_and_saveexec_b64 s[28:29], s[4:5]
	s_cbranch_execz .LBB0_2067
	s_waitcnt lgkmcnt(0)
	v_add_f32_e32 v48, v48, v49
	v_mul_f32_e32 v48, 0x4b800000, v48
	v_trunc_f32_e32 v48, v48
	v_mul_f32_e32 v49, 0x2f800000, v48
	v_floor_f32_e32 v49, v49
	v_fmac_f32_e32 v48, 0xcf800000, v49
	v_cvt_u32_f32_e32 v48, v48
	v_cvt_u32_f32_e32 v49, v49
	v_lshl_add_u64 v[50:51], v[100:101], 3, s[12:13]
	global_atomic_add_x2 v[50:51], v[48:49], off
